# baseline (speedup 1.0000x reference)
.Lglds2_2829:
	ds_read_b128 v[152:155], v112 offset:16384
	ds_read_b128 v[156:159], v110
	ds_read_b128 v[160:163], v112 offset:18432
	ds_read_b128 v[164:167], v112 offset:20480
	ds_read_b128 v[168:171], v113 offset:16384
	ds_read_b128 v[172:175], v110 offset:2048
	ds_read_b128 v[208:211], v110 offset:4096
	ds_read_b128 v[212:215], v111
	ds_read_b128 v[216:219], v116 offset:16384
	ds_read_b128 v[220:223], v114
	ds_read_b128 v[224:227], v116 offset:18432
	ds_read_b128 v[228:231], v116 offset:20480
	ds_read_b128 v[232:235], v117 offset:16384
	ds_read_b128 v[236:239], v114 offset:2048
	ds_read_b128 v[240:243], v114 offset:4096
	ds_read_b128 v[244:247], v115
	s_setprio 1
	s_waitcnt lgkmcnt(14)
	v_mfma_f32_16x16x32_bf16 v[94:97], v[152:155], v[156:159], v[94:97]
	s_waitcnt lgkmcnt(13)
	v_mfma_f32_16x16x32_bf16 v[90:93], v[160:163], v[156:159], v[90:93]
	s_waitcnt lgkmcnt(12)
	v_mfma_f32_16x16x32_bf16 v[86:89], v[164:167], v[156:159], v[86:89]
	s_waitcnt lgkmcnt(11)
	v_mfma_f32_16x16x32_bf16 v[82:85], v[168:171], v[156:159], v[82:85]
	s_waitcnt lgkmcnt(10)
	v_mfma_f32_16x16x32_bf16 v[78:81], v[152:155], v[172:175], v[78:81]
	v_mfma_f32_16x16x32_bf16 v[62:65], v[160:163], v[172:175], v[62:65]
	v_mfma_f32_16x16x32_bf16 v[46:49], v[164:167], v[172:175], v[46:49]
	v_mfma_f32_16x16x32_bf16 v[26:29], v[168:171], v[172:175], v[26:29]
	s_waitcnt lgkmcnt(9)
	v_mfma_f32_16x16x32_bf16 v[38:41], v[152:155], v[208:211], v[38:41]
	v_mfma_f32_16x16x32_bf16 v[30:33], v[160:163], v[208:211], v[30:33]
	v_mfma_f32_16x16x32_bf16 v[22:25], v[164:167], v[208:211], v[22:25]
	v_mfma_f32_16x16x32_bf16 v[18:21], v[168:171], v[208:211], v[18:21]
	s_waitcnt lgkmcnt(8)
	v_mfma_f32_16x16x32_bf16 v[14:17], v[152:155], v[212:215], v[14:17]
	v_mfma_f32_16x16x32_bf16 v[10:13], v[160:163], v[212:215], v[10:13]
	v_mfma_f32_16x16x32_bf16 v[6:9], v[164:167], v[212:215], v[6:9]
	v_mfma_f32_16x16x32_bf16 v[2:5], v[168:171], v[212:215], v[2:5]
	s_waitcnt lgkmcnt(0)
	s_add_i32 s0, s5, 0x80
	s_min_u32 s0, s0, 0x3c0
	s_lshl_b32 s0, s0, 1
	v_mfma_f32_16x16x32_bf16 v[94:97], v[216:219], v[220:223], v[94:97]
	v_mfma_f32_16x16x32_bf16 v[90:93], v[224:227], v[220:223], v[90:93]
	v_mfma_f32_16x16x32_bf16 v[86:89], v[228:231], v[220:223], v[86:89]
	v_mfma_f32_16x16x32_bf16 v[82:85], v[232:235], v[220:223], v[82:85]
	s_setprio 0
	s_barrier
	s_setprio 1
	v_mfma_f32_16x16x32_bf16 v[78:81], v[216:219], v[236:239], v[78:81]
	s_add_u32 m0, s6, 0x0
	v_lshl_add_u64 v[204:205], v[188:189], 0, s[0:1]
	global_load_lds_dwordx4 v[204:205], off
	v_mfma_f32_16x16x32_bf16 v[62:65], v[224:227], v[236:239], v[62:65]
	v_mfma_f32_16x16x32_bf16 v[46:49], v[228:231], v[236:239], v[46:49]
	s_add_u32 m0, s6, 0x1000
	v_lshl_add_u64 v[206:207], v[190:191], 0, s[0:1]
	global_load_lds_dwordx4 v[206:207], off
	v_mfma_f32_16x16x32_bf16 v[26:29], v[232:235], v[236:239], v[26:29]
	v_mfma_f32_16x16x32_bf16 v[38:41], v[216:219], v[240:243], v[38:41]
	s_add_u32 m0, s6, 0x2000
	v_lshl_add_u64 v[204:205], v[192:193], 0, s[0:1]
	global_load_lds_dwordx4 v[204:205], off
	v_mfma_f32_16x16x32_bf16 v[30:33], v[224:227], v[240:243], v[30:33]
	v_mfma_f32_16x16x32_bf16 v[22:25], v[228:231], v[240:243], v[22:25]
	s_add_u32 m0, s6, 0x3000
	v_lshl_add_u64 v[206:207], v[194:195], 0, s[0:1]
	global_load_lds_dwordx4 v[206:207], off
	v_mfma_f32_16x16x32_bf16 v[18:21], v[232:235], v[240:243], v[18:21]
	v_mfma_f32_16x16x32_bf16 v[14:17], v[216:219], v[244:247], v[14:17]
	s_add_u32 m0, s6, 0x4000
	v_lshl_add_u64 v[204:205], v[196:197], 0, s[0:1]
	global_load_lds_dwordx4 v[204:205], off
	v_mfma_f32_16x16x32_bf16 v[10:13], v[224:227], v[244:247], v[10:13]
	s_add_u32 m0, s6, 0x5000
	v_lshl_add_u64 v[206:207], v[198:199], 0, s[0:1]
	global_load_lds_dwordx4 v[206:207], off
	v_mfma_f32_16x16x32_bf16 v[6:9], v[228:231], v[244:247], v[6:9]
	s_add_u32 m0, s6, 0x6000
	v_lshl_add_u64 v[204:205], v[200:201], 0, s[0:1]
	global_load_lds_dwordx4 v[204:205], off
	v_mfma_f32_16x16x32_bf16 v[2:5], v[232:235], v[244:247], v[2:5]
	s_add_u32 m0, s6, 0x7000
	v_lshl_add_u64 v[206:207], v[202:203], 0, s[0:1]
	global_load_lds_dwordx4 v[206:207], off
	s_setprio 0
	s_waitcnt vmcnt(8)
	s_barrier
	ds_read_b128 v[152:155], v112 offset:49152
	ds_read_b128 v[156:159], v110 offset:32768
	ds_read_b128 v[160:163], v112 offset:51200
	ds_read_b128 v[164:167], v112 offset:53248
	ds_read_b128 v[168:171], v113 offset:49152
	ds_read_b128 v[172:175], v110 offset:34816
	ds_read_b128 v[208:211], v110 offset:36864
	ds_read_b128 v[212:215], v111 offset:32768
	ds_read_b128 v[216:219], v116 offset:49152
	ds_read_b128 v[220:223], v114 offset:32768
	ds_read_b128 v[224:227], v116 offset:51200
	ds_read_b128 v[228:231], v116 offset:53248
	ds_read_b128 v[232:235], v117 offset:49152
	ds_read_b128 v[236:239], v114 offset:34816
	ds_read_b128 v[240:243], v114 offset:36864
	ds_read_b128 v[244:247], v115 offset:32768
	s_setprio 1
	s_waitcnt lgkmcnt(14)
	v_mfma_f32_16x16x32_bf16 v[94:97], v[152:155], v[156:159], v[94:97]
	s_waitcnt lgkmcnt(13)
	v_mfma_f32_16x16x32_bf16 v[90:93], v[160:163], v[156:159], v[90:93]
	s_waitcnt lgkmcnt(12)
	v_mfma_f32_16x16x32_bf16 v[86:89], v[164:167], v[156:159], v[86:89]
	s_waitcnt lgkmcnt(11)
	v_mfma_f32_16x16x32_bf16 v[82:85], v[168:171], v[156:159], v[82:85]
	s_waitcnt lgkmcnt(10)
	v_mfma_f32_16x16x32_bf16 v[78:81], v[152:155], v[172:175], v[78:81]
	v_mfma_f32_16x16x32_bf16 v[62:65], v[160:163], v[172:175], v[62:65]
	v_mfma_f32_16x16x32_bf16 v[46:49], v[164:167], v[172:175], v[46:49]
	v_mfma_f32_16x16x32_bf16 v[26:29], v[168:171], v[172:175], v[26:29]
	s_waitcnt lgkmcnt(9)
	v_mfma_f32_16x16x32_bf16 v[38:41], v[152:155], v[208:211], v[38:41]
	v_mfma_f32_16x16x32_bf16 v[30:33], v[160:163], v[208:211], v[30:33]
	v_mfma_f32_16x16x32_bf16 v[22:25], v[164:167], v[208:211], v[22:25]
	v_mfma_f32_16x16x32_bf16 v[18:21], v[168:171], v[208:211], v[18:21]
	s_waitcnt lgkmcnt(8)
	v_mfma_f32_16x16x32_bf16 v[14:17], v[152:155], v[212:215], v[14:17]
	v_mfma_f32_16x16x32_bf16 v[10:13], v[160:163], v[212:215], v[10:13]
	v_mfma_f32_16x16x32_bf16 v[6:9], v[164:167], v[212:215], v[6:9]
	v_mfma_f32_16x16x32_bf16 v[2:5], v[168:171], v[212:215], v[2:5]
	s_waitcnt lgkmcnt(0)
	s_add_i32 s0, s5, 0xc0
	s_min_u32 s0, s0, 0x3c0
	s_lshl_b32 s0, s0, 1
	v_mfma_f32_16x16x32_bf16 v[94:97], v[216:219], v[220:223], v[94:97]
	v_mfma_f32_16x16x32_bf16 v[90:93], v[224:227], v[220:223], v[90:93]
	v_mfma_f32_16x16x32_bf16 v[86:89], v[228:231], v[220:223], v[86:89]
	v_mfma_f32_16x16x32_bf16 v[82:85], v[232:235], v[220:223], v[82:85]
	s_setprio 0
	s_barrier
	s_setprio 1
	v_mfma_f32_16x16x32_bf16 v[78:81], v[216:219], v[236:239], v[78:81]
	s_add_u32 m0, s6, 0x8000
	v_lshl_add_u64 v[204:205], v[188:189], 0, s[0:1]
	global_load_lds_dwordx4 v[204:205], off
	v_mfma_f32_16x16x32_bf16 v[62:65], v[224:227], v[236:239], v[62:65]
	v_mfma_f32_16x16x32_bf16 v[46:49], v[228:231], v[236:239], v[46:49]
	s_add_u32 m0, s6, 0x9000
	v_lshl_add_u64 v[206:207], v[190:191], 0, s[0:1]
	global_load_lds_dwordx4 v[206:207], off
	v_mfma_f32_16x16x32_bf16 v[26:29], v[232:235], v[236:239], v[26:29]
	v_mfma_f32_16x16x32_bf16 v[38:41], v[216:219], v[240:243], v[38:41]
	s_add_u32 m0, s6, 0xa000
	v_lshl_add_u64 v[204:205], v[192:193], 0, s[0:1]
	global_load_lds_dwordx4 v[204:205], off
	v_mfma_f32_16x16x32_bf16 v[30:33], v[224:227], v[240:243], v[30:33]
	v_mfma_f32_16x16x32_bf16 v[22:25], v[228:231], v[240:243], v[22:25]
	s_add_u32 m0, s6, 0xb000
	v_lshl_add_u64 v[206:207], v[194:195], 0, s[0:1]
	global_load_lds_dwordx4 v[206:207], off
	v_mfma_f32_16x16x32_bf16 v[18:21], v[232:235], v[240:243], v[18:21]
	v_mfma_f32_16x16x32_bf16 v[14:17], v[216:219], v[244:247], v[14:17]
	s_add_u32 m0, s6, 0xc000
	v_lshl_add_u64 v[204:205], v[196:197], 0, s[0:1]
	global_load_lds_dwordx4 v[204:205], off
	v_mfma_f32_16x16x32_bf16 v[10:13], v[224:227], v[244:247], v[10:13]
	s_add_u32 m0, s6, 0xd000
	v_lshl_add_u64 v[206:207], v[198:199], 0, s[0:1]
	global_load_lds_dwordx4 v[206:207], off
	v_mfma_f32_16x16x32_bf16 v[6:9], v[228:231], v[244:247], v[6:9]
	s_add_u32 m0, s6, 0xe000
	v_lshl_add_u64 v[204:205], v[200:201], 0, s[0:1]
	global_load_lds_dwordx4 v[204:205], off
	v_mfma_f32_16x16x32_bf16 v[2:5], v[232:235], v[244:247], v[2:5]
	s_add_u32 m0, s6, 0xf000
	v_lshl_add_u64 v[206:207], v[202:203], 0, s[0:1]
	global_load_lds_dwordx4 v[206:207], off
	s_setprio 0
	s_waitcnt vmcnt(8)
	s_barrier
	s_add_i32 s5, s5, 0x80
	s_add_i32 s4, s4, 2
	s_cmp_gt_u32 s4, 13
	s_cbranch_scc0 .Lglds2_2829
	s_waitcnt vmcnt(0)
	v_readlane_b32 s36, v254, 40
	s_waitcnt vmcnt(7)
	v_or_b32_e32 v35, s2, v118
	v_readlane_b32 s48, v254, 52
	v_readlane_b32 s49, v254, 53
	v_or_b32_e32 v34, s3, v119
	s_waitcnt vmcnt(6)
	v_add_u32_e32 v42, v35, v120
	v_mov_b64_e32 v[36:37], s[48:49]
	v_mad_i64_i32 v[36:37], s[2:3], v42, s18, v[36:37]
	v_cmp_gt_i32_e32 vcc, s19, v34
	v_ashrrev_i32_e32 v35, 31, v34
	v_readlane_b32 s37, v254, 41
	v_readlane_b32 s38, v254, 42
	v_readlane_b32 s39, v254, 43
	v_readlane_b32 s40, v254, 44
	v_readlane_b32 s41, v254, 45
	v_readlane_b32 s42, v254, 46
	v_readlane_b32 s43, v254, 47
	v_readlane_b32 s44, v254, 48
	v_readlane_b32 s45, v254, 49
	v_readlane_b32 s46, v254, 50
	v_readlane_b32 s47, v254, 51
	v_readlane_b32 s50, v254, 54
	v_readlane_b32 s51, v254, 55
	s_and_saveexec_b64 s[2:3], vcc
	s_cbranch_execnz .LBB0_205
	s_or_b64 exec, exec, s[2:3]
	v_cmp_gt_i32_e64 s[4:5], s20, v34
	s_and_saveexec_b64 s[2:3], s[4:5]
	s_cbranch_execnz .LBB0_206

.Lglds2_3547:
	ds_read_b128 v[152:155], v112 offset:16384
	ds_read_b128 v[156:159], v110
	ds_read_b128 v[160:163], v112 offset:18432
	ds_read_b128 v[164:167], v112 offset:20480
	ds_read_b128 v[168:171], v113 offset:16384
	ds_read_b128 v[172:175], v110 offset:2048
	ds_read_b128 v[208:211], v110 offset:4096
	ds_read_b128 v[212:215], v111
	ds_read_b128 v[216:219], v116 offset:16384
	ds_read_b128 v[220:223], v114
	ds_read_b128 v[224:227], v116 offset:18432
	ds_read_b128 v[228:231], v116 offset:20480
	ds_read_b128 v[232:235], v117 offset:16384
	ds_read_b128 v[236:239], v114 offset:2048
	ds_read_b128 v[240:243], v114 offset:4096
	ds_read_b128 v[244:247], v115
	s_setprio 1
	s_waitcnt lgkmcnt(14)
	v_mfma_f32_16x16x32_bf16 v[94:97], v[152:155], v[156:159], v[94:97]
	s_waitcnt lgkmcnt(13)
	v_mfma_f32_16x16x32_bf16 v[90:93], v[160:163], v[156:159], v[90:93]
	s_waitcnt lgkmcnt(12)
	v_mfma_f32_16x16x32_bf16 v[86:89], v[164:167], v[156:159], v[86:89]
	s_waitcnt lgkmcnt(11)
	v_mfma_f32_16x16x32_bf16 v[82:85], v[168:171], v[156:159], v[82:85]
	s_waitcnt lgkmcnt(10)
	v_mfma_f32_16x16x32_bf16 v[78:81], v[152:155], v[172:175], v[78:81]
	v_mfma_f32_16x16x32_bf16 v[54:57], v[160:163], v[172:175], v[54:57]
	v_mfma_f32_16x16x32_bf16 v[38:41], v[164:167], v[172:175], v[38:41]
	v_mfma_f32_16x16x32_bf16 v[34:37], v[168:171], v[172:175], v[34:37]
	s_waitcnt lgkmcnt(9)
	v_mfma_f32_16x16x32_bf16 v[74:77], v[152:155], v[208:211], v[74:77]
	v_mfma_f32_16x16x32_bf16 v[70:73], v[160:163], v[208:211], v[70:73]
	v_mfma_f32_16x16x32_bf16 v[66:69], v[164:167], v[208:211], v[66:69]
	v_mfma_f32_16x16x32_bf16 v[62:65], v[168:171], v[208:211], v[62:65]
	s_waitcnt lgkmcnt(8)
	v_mfma_f32_16x16x32_bf16 v[58:61], v[152:155], v[212:215], v[58:61]
	v_mfma_f32_16x16x32_bf16 v[50:53], v[160:163], v[212:215], v[50:53]
	v_mfma_f32_16x16x32_bf16 v[46:49], v[164:167], v[212:215], v[46:49]
	v_mfma_f32_16x16x32_bf16 v[42:45], v[168:171], v[212:215], v[42:45]
	s_waitcnt lgkmcnt(0)
	s_add_i32 s0, s19, 0x80
	s_min_u32 s0, s0, 0x3c0
	s_lshl_b32 s0, s0, 1
	v_mfma_f32_16x16x32_bf16 v[94:97], v[216:219], v[220:223], v[94:97]
	v_mfma_f32_16x16x32_bf16 v[90:93], v[224:227], v[220:223], v[90:93]
	v_mfma_f32_16x16x32_bf16 v[86:89], v[228:231], v[220:223], v[86:89]
	v_mfma_f32_16x16x32_bf16 v[82:85], v[232:235], v[220:223], v[82:85]
	s_setprio 0
	s_barrier
	s_setprio 1
	v_mfma_f32_16x16x32_bf16 v[78:81], v[216:219], v[236:239], v[78:81]
	s_add_u32 m0, s20, 0x0
	v_lshl_add_u64 v[204:205], v[188:189], 0, s[0:1]
	global_load_lds_dwordx4 v[204:205], off
	v_mfma_f32_16x16x32_bf16 v[54:57], v[224:227], v[236:239], v[54:57]
	v_mfma_f32_16x16x32_bf16 v[38:41], v[228:231], v[236:239], v[38:41]
	s_add_u32 m0, s20, 0x1000
	v_lshl_add_u64 v[206:207], v[190:191], 0, s[0:1]
	global_load_lds_dwordx4 v[206:207], off
	v_mfma_f32_16x16x32_bf16 v[34:37], v[232:235], v[236:239], v[34:37]
	v_mfma_f32_16x16x32_bf16 v[74:77], v[216:219], v[240:243], v[74:77]
	s_add_u32 m0, s20, 0x2000
	v_lshl_add_u64 v[204:205], v[192:193], 0, s[0:1]
	global_load_lds_dwordx4 v[204:205], off
	v_mfma_f32_16x16x32_bf16 v[70:73], v[224:227], v[240:243], v[70:73]
	v_mfma_f32_16x16x32_bf16 v[66:69], v[228:231], v[240:243], v[66:69]
	s_add_u32 m0, s20, 0x3000
	v_lshl_add_u64 v[206:207], v[194:195], 0, s[0:1]
	global_load_lds_dwordx4 v[206:207], off
	v_mfma_f32_16x16x32_bf16 v[62:65], v[232:235], v[240:243], v[62:65]
	v_mfma_f32_16x16x32_bf16 v[58:61], v[216:219], v[244:247], v[58:61]
	s_add_u32 m0, s20, 0x4000
	v_lshl_add_u64 v[204:205], v[196:197], 0, s[0:1]
	global_load_lds_dwordx4 v[204:205], off
	v_mfma_f32_16x16x32_bf16 v[50:53], v[224:227], v[244:247], v[50:53]
	s_add_u32 m0, s20, 0x5000
	v_lshl_add_u64 v[206:207], v[198:199], 0, s[0:1]
	global_load_lds_dwordx4 v[206:207], off
	v_mfma_f32_16x16x32_bf16 v[46:49], v[228:231], v[244:247], v[46:49]
	s_add_u32 m0, s20, 0x6000
	v_lshl_add_u64 v[204:205], v[200:201], 0, s[0:1]
	global_load_lds_dwordx4 v[204:205], off
	v_mfma_f32_16x16x32_bf16 v[42:45], v[232:235], v[244:247], v[42:45]
	s_add_u32 m0, s20, 0x7000
	v_lshl_add_u64 v[206:207], v[202:203], 0, s[0:1]
	global_load_lds_dwordx4 v[206:207], off
	s_setprio 0
	s_waitcnt vmcnt(8)
	s_barrier
	ds_read_b128 v[152:155], v112 offset:49152
	ds_read_b128 v[156:159], v110 offset:32768
	ds_read_b128 v[160:163], v112 offset:51200
	ds_read_b128 v[164:167], v112 offset:53248
	ds_read_b128 v[168:171], v113 offset:49152
	ds_read_b128 v[172:175], v110 offset:34816
	ds_read_b128 v[208:211], v110 offset:36864
	ds_read_b128 v[212:215], v111 offset:32768
	ds_read_b128 v[216:219], v116 offset:49152
	ds_read_b128 v[220:223], v114 offset:32768
	ds_read_b128 v[224:227], v116 offset:51200
	ds_read_b128 v[228:231], v116 offset:53248
	ds_read_b128 v[232:235], v117 offset:49152
	ds_read_b128 v[236:239], v114 offset:34816
	ds_read_b128 v[240:243], v114 offset:36864
	ds_read_b128 v[244:247], v115 offset:32768
	s_setprio 1
	s_waitcnt lgkmcnt(14)
	v_mfma_f32_16x16x32_bf16 v[94:97], v[152:155], v[156:159], v[94:97]
	s_waitcnt lgkmcnt(13)
	v_mfma_f32_16x16x32_bf16 v[90:93], v[160:163], v[156:159], v[90:93]
	s_waitcnt lgkmcnt(12)
	v_mfma_f32_16x16x32_bf16 v[86:89], v[164:167], v[156:159], v[86:89]
	s_waitcnt lgkmcnt(11)
	v_mfma_f32_16x16x32_bf16 v[82:85], v[168:171], v[156:159], v[82:85]
	s_waitcnt lgkmcnt(10)
	v_mfma_f32_16x16x32_bf16 v[78:81], v[152:155], v[172:175], v[78:81]
	v_mfma_f32_16x16x32_bf16 v[54:57], v[160:163], v[172:175], v[54:57]
	v_mfma_f32_16x16x32_bf16 v[38:41], v[164:167], v[172:175], v[38:41]
	v_mfma_f32_16x16x32_bf16 v[34:37], v[168:171], v[172:175], v[34:37]
	s_waitcnt lgkmcnt(9)
	v_mfma_f32_16x16x32_bf16 v[74:77], v[152:155], v[208:211], v[74:77]
	v_mfma_f32_16x16x32_bf16 v[70:73], v[160:163], v[208:211], v[70:73]
	v_mfma_f32_16x16x32_bf16 v[66:69], v[164:167], v[208:211], v[66:69]
	v_mfma_f32_16x16x32_bf16 v[62:65], v[168:171], v[208:211], v[62:65]
	s_waitcnt lgkmcnt(8)
	v_mfma_f32_16x16x32_bf16 v[58:61], v[152:155], v[212:215], v[58:61]
	v_mfma_f32_16x16x32_bf16 v[50:53], v[160:163], v[212:215], v[50:53]
	v_mfma_f32_16x16x32_bf16 v[46:49], v[164:167], v[212:215], v[46:49]
	v_mfma_f32_16x16x32_bf16 v[42:45], v[168:171], v[212:215], v[42:45]
	s_waitcnt lgkmcnt(0)
	s_add_i32 s0, s19, 0xc0
	s_min_u32 s0, s0, 0x3c0
	s_lshl_b32 s0, s0, 1
	v_mfma_f32_16x16x32_bf16 v[94:97], v[216:219], v[220:223], v[94:97]
	v_mfma_f32_16x16x32_bf16 v[90:93], v[224:227], v[220:223], v[90:93]
	v_mfma_f32_16x16x32_bf16 v[86:89], v[228:231], v[220:223], v[86:89]
	v_mfma_f32_16x16x32_bf16 v[82:85], v[232:235], v[220:223], v[82:85]
	s_setprio 0
	s_barrier
	s_setprio 1
	v_mfma_f32_16x16x32_bf16 v[78:81], v[216:219], v[236:239], v[78:81]
	s_add_u32 m0, s20, 0x8000
	v_lshl_add_u64 v[204:205], v[188:189], 0, s[0:1]
	global_load_lds_dwordx4 v[204:205], off
	v_mfma_f32_16x16x32_bf16 v[54:57], v[224:227], v[236:239], v[54:57]
	v_mfma_f32_16x16x32_bf16 v[38:41], v[228:231], v[236:239], v[38:41]
	s_add_u32 m0, s20, 0x9000
	v_lshl_add_u64 v[206:207], v[190:191], 0, s[0:1]
	global_load_lds_dwordx4 v[206:207], off
	v_mfma_f32_16x16x32_bf16 v[34:37], v[232:235], v[236:239], v[34:37]
	v_mfma_f32_16x16x32_bf16 v[74:77], v[216:219], v[240:243], v[74:77]
	s_add_u32 m0, s20, 0xa000
	v_lshl_add_u64 v[204:205], v[192:193], 0, s[0:1]
	global_load_lds_dwordx4 v[204:205], off
	v_mfma_f32_16x16x32_bf16 v[70:73], v[224:227], v[240:243], v[70:73]
	v_mfma_f32_16x16x32_bf16 v[66:69], v[228:231], v[240:243], v[66:69]
	s_add_u32 m0, s20, 0xb000
	v_lshl_add_u64 v[206:207], v[194:195], 0, s[0:1]
	global_load_lds_dwordx4 v[206:207], off
	v_mfma_f32_16x16x32_bf16 v[62:65], v[232:235], v[240:243], v[62:65]
	v_mfma_f32_16x16x32_bf16 v[58:61], v[216:219], v[244:247], v[58:61]
	s_add_u32 m0, s20, 0xc000
	v_lshl_add_u64 v[204:205], v[196:197], 0, s[0:1]
	global_load_lds_dwordx4 v[204:205], off
	v_mfma_f32_16x16x32_bf16 v[50:53], v[224:227], v[244:247], v[50:53]
	s_add_u32 m0, s20, 0xd000
	v_lshl_add_u64 v[206:207], v[198:199], 0, s[0:1]
	global_load_lds_dwordx4 v[206:207], off
	v_mfma_f32_16x16x32_bf16 v[46:49], v[228:231], v[244:247], v[46:49]
	s_add_u32 m0, s20, 0xe000
	v_lshl_add_u64 v[204:205], v[200:201], 0, s[0:1]
	global_load_lds_dwordx4 v[204:205], off
	v_mfma_f32_16x16x32_bf16 v[42:45], v[232:235], v[244:247], v[42:45]
	s_add_u32 m0, s20, 0xf000
	v_lshl_add_u64 v[206:207], v[202:203], 0, s[0:1]
	global_load_lds_dwordx4 v[206:207], off
	s_setprio 0
	s_waitcnt vmcnt(8)
	s_barrier
	s_add_i32 s19, s19, 0x80
	s_add_i32 s18, s18, 2
	s_cmp_lt_u32 s18, 14
	s_cbranch_scc1 .Lglds2_3547
	s_waitcnt vmcnt(0)
	v_readlane_b32 s36, v254, 40
	s_lshl_b64 s[12:13], s[12:13], 21
	v_readlane_b32 s50, v254, 54
	v_readlane_b32 s51, v254, 55
	s_add_u32 s12, s50, s12
	s_addc_u32 s13, s51, s13
	s_waitcnt vmcnt(7)
	v_or_b32_e32 v4, s17, v119
	v_add_lshl_u32 v98, v118, s16, 10
	v_lshl_add_u64 v[2:3], s[12:13], 0, v[98:99]
	v_lshlrev_b32_e32 v98, 1, v4
	v_lshl_add_u64 v[4:5], v[2:3], 0, v[98:99]
	s_waitcnt vmcnt(6)
	v_cvt_pk_bf16_f32 v6, v94, v95
	v_cvt_pk_bf16_f32 v7, v96, v97
	global_store_dwordx2 v[4:5], v[6:7], off
	v_cvt_pk_bf16_f32 v6, v90, v91
	v_cvt_pk_bf16_f32 v7, v92, v93
	global_store_dwordx2 v[4:5], v[6:7], off offset:32
	v_cvt_pk_bf16_f32 v6, v86, v87
	v_cvt_pk_bf16_f32 v7, v88, v89
	global_store_dwordx2 v[4:5], v[6:7], off offset:64
	v_cvt_pk_bf16_f32 v6, v82, v83
	v_cvt_pk_bf16_f32 v7, v84, v85
	global_store_dwordx2 v[4:5], v[6:7], off offset:96
	v_lshl_add_u64 v[4:5], v[2:3], 0, s[4:5]
	v_lshl_add_u64 v[6:7], v[4:5], 0, v[98:99]
	v_cvt_pk_bf16_f32 v8, v78, v79
	v_cvt_pk_bf16_f32 v9, v80, v81
	global_store_dwordx2 v[6:7], v[8:9], off
	v_or_b32_e32 v6, 32, v98
	v_mov_b32_e32 v7, v99
	v_lshl_add_u64 v[8:9], v[4:5], 0, v[6:7]
	s_waitcnt vmcnt(10)
	v_cvt_pk_bf16_f32 v10, v54, v55
	v_cvt_pk_bf16_f32 v11, v56, v57
	global_store_dwordx2 v[8:9], v[10:11], off
	v_or_b32_e32 v8, 64, v98
	v_mov_b32_e32 v9, v99
	v_lshl_add_u64 v[10:11], v[4:5], 0, v[8:9]
	v_cvt_pk_bf16_f32 v12, v38, v39
	v_cvt_pk_bf16_f32 v13, v40, v41
	global_store_dwordx2 v[10:11], v[12:13], off
	v_or_b32_e32 v10, 0x60, v98
	v_mov_b32_e32 v11, v99
	v_lshl_add_u64 v[4:5], v[4:5], 0, v[10:11]
	v_cvt_pk_bf16_f32 v12, v34, v35
	v_cvt_pk_bf16_f32 v13, v36, v37
	global_store_dwordx2 v[4:5], v[12:13], off
	v_lshl_add_u64 v[4:5], v[2:3], 0, s[6:7]
	v_lshl_add_u64 v[12:13], v[4:5], 0, v[98:99]
	s_waitcnt vmcnt(11)
	v_cvt_pk_bf16_f32 v14, v74, v75
	v_cvt_pk_bf16_f32 v15, v76, v77
	global_store_dwordx2 v[12:13], v[14:15], off
	v_lshl_add_u64 v[12:13], v[4:5], 0, v[6:7]
	v_cvt_pk_bf16_f32 v14, v70, v71
	v_cvt_pk_bf16_f32 v15, v72, v73
	global_store_dwordx2 v[12:13], v[14:15], off
	v_lshl_add_u64 v[12:13], v[4:5], 0, v[8:9]
	v_cvt_pk_bf16_f32 v14, v66, v67
	v_cvt_pk_bf16_f32 v15, v68, v69
	global_store_dwordx2 v[12:13], v[14:15], off
	v_lshl_add_u64 v[4:5], v[4:5], 0, v[10:11]
	v_cvt_pk_bf16_f32 v12, v62, v63
	v_cvt_pk_bf16_f32 v13, v64, v65
	v_lshl_add_u64 v[2:3], v[2:3], 0, s[8:9]
	global_store_dwordx2 v[4:5], v[12:13], off
	v_lshl_add_u64 v[4:5], v[2:3], 0, v[98:99]
	v_cvt_pk_bf16_f32 v12, v58, v59
	v_cvt_pk_bf16_f32 v13, v60, v61
	global_store_dwordx2 v[4:5], v[12:13], off
	v_lshl_add_u64 v[4:5], v[2:3], 0, v[6:7]
	v_cvt_pk_bf16_f32 v6, v50, v51
	v_cvt_pk_bf16_f32 v7, v52, v53
	v_readlane_b32 s12, v254, 0
	global_store_dwordx2 v[4:5], v[6:7], off
	v_lshl_add_u64 v[4:5], v[2:3], 0, v[8:9]
	v_cvt_pk_bf16_f32 v6, v46, v47
	v_cvt_pk_bf16_f32 v7, v48, v49
	s_add_i32 s2, s2, s12
	v_readlane_b32 s37, v254, 41
	global_store_dwordx2 v[4:5], v[6:7], off
	v_lshl_add_u64 v[2:3], v[2:3], 0, v[10:11]
	v_cvt_pk_bf16_f32 v4, v42, v43
	v_cvt_pk_bf16_f32 v5, v44, v45
	s_cmpk_lt_i32 s2, 0x80
	v_readlane_b32 s38, v254, 42
	v_readlane_b32 s39, v254, 43
	v_readlane_b32 s40, v254, 44
	v_readlane_b32 s41, v254, 45
	v_readlane_b32 s42, v254, 46
	v_readlane_b32 s43, v254, 47
	v_readlane_b32 s44, v254, 48
	v_readlane_b32 s45, v254, 49
	v_readlane_b32 s46, v254, 50
	v_readlane_b32 s47, v254, 51
	v_readlane_b32 s48, v254, 52
	v_readlane_b32 s49, v254, 53
	v_readlane_b32 s13, v254, 1
	global_store_dwordx2 v[2:3], v[4:5], off
	s_cbranch_scc1 .LBB0_220

.Lglds2_12468:
	ds_read_b128 v[152:155], v112 offset:16384
	ds_read_b128 v[156:159], v110
	ds_read_b128 v[160:163], v112 offset:18432
	ds_read_b128 v[164:167], v112 offset:20480
	ds_read_b128 v[168:171], v113 offset:16384
	ds_read_b128 v[172:175], v110 offset:2048
	ds_read_b128 v[204:207], v110 offset:4096
	ds_read_b128 v[208:211], v111
	ds_read_b128 v[212:215], v116 offset:16384
	ds_read_b128 v[216:219], v114
	ds_read_b128 v[220:223], v116 offset:18432
	ds_read_b128 v[224:227], v116 offset:20480
	ds_read_b128 v[228:231], v117 offset:16384
	ds_read_b128 v[232:235], v114 offset:2048
	ds_read_b128 v[236:239], v114 offset:4096
	ds_read_b128 v[240:243], v115
	s_setprio 1
	s_waitcnt lgkmcnt(14)
	v_mfma_f32_16x16x32_bf16 v[94:97], v[152:155], v[156:159], v[94:97]
	s_waitcnt lgkmcnt(13)
	v_mfma_f32_16x16x32_bf16 v[90:93], v[160:163], v[156:159], v[90:93]
	s_waitcnt lgkmcnt(12)
	v_mfma_f32_16x16x32_bf16 v[86:89], v[164:167], v[156:159], v[86:89]
	s_waitcnt lgkmcnt(11)
	v_mfma_f32_16x16x32_bf16 v[82:85], v[168:171], v[156:159], v[82:85]
	s_waitcnt lgkmcnt(10)
	v_mfma_f32_16x16x32_bf16 v[78:81], v[152:155], v[172:175], v[78:81]
	v_mfma_f32_16x16x32_bf16 v[74:77], v[160:163], v[172:175], v[74:77]
	v_mfma_f32_16x16x32_bf16 v[62:65], v[164:167], v[172:175], v[62:65]
	v_mfma_f32_16x16x32_bf16 v[30:33], v[168:171], v[172:175], v[30:33]
	s_waitcnt lgkmcnt(9)
	v_mfma_f32_16x16x32_bf16 v[66:69], v[152:155], v[204:207], v[66:69]
	v_mfma_f32_16x16x32_bf16 v[38:41], v[160:163], v[204:207], v[38:41]
	v_mfma_f32_16x16x32_bf16 v[34:37], v[164:167], v[204:207], v[34:37]
	v_mfma_f32_16x16x32_bf16 v[18:21], v[168:171], v[204:207], v[18:21]
	s_waitcnt lgkmcnt(8)
	v_mfma_f32_16x16x32_bf16 v[14:17], v[152:155], v[208:211], v[14:17]
	v_mfma_f32_16x16x32_bf16 v[10:13], v[160:163], v[208:211], v[10:13]
	v_mfma_f32_16x16x32_bf16 v[6:9], v[164:167], v[208:211], v[6:9]
	v_mfma_f32_16x16x32_bf16 v[2:5], v[168:171], v[208:211], v[2:5]
	s_waitcnt lgkmcnt(0)
	s_add_i32 s4, s14, 0x80
	s_min_u32 s4, s4, 0x3c0
	s_lshl_b32 s4, s4, 1
	v_mfma_f32_16x16x32_bf16 v[94:97], v[212:215], v[216:219], v[94:97]
	v_mfma_f32_16x16x32_bf16 v[90:93], v[220:223], v[216:219], v[90:93]
	v_mfma_f32_16x16x32_bf16 v[86:89], v[224:227], v[216:219], v[86:89]
	v_mfma_f32_16x16x32_bf16 v[82:85], v[228:231], v[216:219], v[82:85]
	s_setprio 0
	s_barrier
	s_setprio 1
	v_mfma_f32_16x16x32_bf16 v[78:81], v[212:215], v[232:235], v[78:81]
	s_add_u32 m0, s15, 0x0
	v_lshl_add_u64 v[200:201], v[184:185], 0, s[4:5]
	global_load_lds_dwordx4 v[200:201], off
	v_mfma_f32_16x16x32_bf16 v[74:77], v[220:223], v[232:235], v[74:77]
	v_mfma_f32_16x16x32_bf16 v[62:65], v[224:227], v[232:235], v[62:65]
	s_add_u32 m0, s15, 0x1000
	v_lshl_add_u64 v[202:203], v[186:187], 0, s[4:5]
	global_load_lds_dwordx4 v[202:203], off
	v_mfma_f32_16x16x32_bf16 v[30:33], v[228:231], v[232:235], v[30:33]
	v_mfma_f32_16x16x32_bf16 v[66:69], v[212:215], v[236:239], v[66:69]
	s_add_u32 m0, s15, 0x2000
	v_lshl_add_u64 v[200:201], v[188:189], 0, s[4:5]
	global_load_lds_dwordx4 v[200:201], off
	v_mfma_f32_16x16x32_bf16 v[38:41], v[220:223], v[236:239], v[38:41]
	v_mfma_f32_16x16x32_bf16 v[34:37], v[224:227], v[236:239], v[34:37]
	s_add_u32 m0, s15, 0x3000
	v_lshl_add_u64 v[202:203], v[190:191], 0, s[4:5]
	global_load_lds_dwordx4 v[202:203], off
	v_mfma_f32_16x16x32_bf16 v[18:21], v[228:231], v[236:239], v[18:21]
	v_mfma_f32_16x16x32_bf16 v[14:17], v[212:215], v[240:243], v[14:17]
	s_add_u32 m0, s15, 0x4000
	v_lshl_add_u64 v[200:201], v[192:193], 0, s[4:5]
	global_load_lds_dwordx4 v[200:201], off
	v_mfma_f32_16x16x32_bf16 v[10:13], v[220:223], v[240:243], v[10:13]
	s_add_u32 m0, s15, 0x5000
	v_lshl_add_u64 v[202:203], v[194:195], 0, s[4:5]
	global_load_lds_dwordx4 v[202:203], off
	v_mfma_f32_16x16x32_bf16 v[6:9], v[224:227], v[240:243], v[6:9]
	s_add_u32 m0, s15, 0x6000
	v_lshl_add_u64 v[200:201], v[196:197], 0, s[4:5]
	global_load_lds_dwordx4 v[200:201], off
	v_mfma_f32_16x16x32_bf16 v[2:5], v[228:231], v[240:243], v[2:5]
	s_add_u32 m0, s15, 0x7000
	v_lshl_add_u64 v[202:203], v[198:199], 0, s[4:5]
	global_load_lds_dwordx4 v[202:203], off
	s_setprio 0
	s_waitcnt vmcnt(8)
	s_barrier
	ds_read_b128 v[152:155], v112 offset:49152
	ds_read_b128 v[156:159], v110 offset:32768
	ds_read_b128 v[160:163], v112 offset:51200
	ds_read_b128 v[164:167], v112 offset:53248
	ds_read_b128 v[168:171], v113 offset:49152
	ds_read_b128 v[172:175], v110 offset:34816
	ds_read_b128 v[204:207], v110 offset:36864
	ds_read_b128 v[208:211], v111 offset:32768
	ds_read_b128 v[212:215], v116 offset:49152
	ds_read_b128 v[216:219], v114 offset:32768
	ds_read_b128 v[220:223], v116 offset:51200
	ds_read_b128 v[224:227], v116 offset:53248
	ds_read_b128 v[228:231], v117 offset:49152
	ds_read_b128 v[232:235], v114 offset:34816
	ds_read_b128 v[236:239], v114 offset:36864
	ds_read_b128 v[240:243], v115 offset:32768
	s_setprio 1
	s_waitcnt lgkmcnt(14)
	v_mfma_f32_16x16x32_bf16 v[94:97], v[152:155], v[156:159], v[94:97]
	s_waitcnt lgkmcnt(13)
	v_mfma_f32_16x16x32_bf16 v[90:93], v[160:163], v[156:159], v[90:93]
	s_waitcnt lgkmcnt(12)
	v_mfma_f32_16x16x32_bf16 v[86:89], v[164:167], v[156:159], v[86:89]
	s_waitcnt lgkmcnt(11)
	v_mfma_f32_16x16x32_bf16 v[82:85], v[168:171], v[156:159], v[82:85]
	s_waitcnt lgkmcnt(10)
	v_mfma_f32_16x16x32_bf16 v[78:81], v[152:155], v[172:175], v[78:81]
	v_mfma_f32_16x16x32_bf16 v[74:77], v[160:163], v[172:175], v[74:77]
	v_mfma_f32_16x16x32_bf16 v[62:65], v[164:167], v[172:175], v[62:65]
	v_mfma_f32_16x16x32_bf16 v[30:33], v[168:171], v[172:175], v[30:33]
	s_waitcnt lgkmcnt(9)
	v_mfma_f32_16x16x32_bf16 v[66:69], v[152:155], v[204:207], v[66:69]
	v_mfma_f32_16x16x32_bf16 v[38:41], v[160:163], v[204:207], v[38:41]
	v_mfma_f32_16x16x32_bf16 v[34:37], v[164:167], v[204:207], v[34:37]
	v_mfma_f32_16x16x32_bf16 v[18:21], v[168:171], v[204:207], v[18:21]
	s_waitcnt lgkmcnt(8)
	v_mfma_f32_16x16x32_bf16 v[14:17], v[152:155], v[208:211], v[14:17]
	v_mfma_f32_16x16x32_bf16 v[10:13], v[160:163], v[208:211], v[10:13]
	v_mfma_f32_16x16x32_bf16 v[6:9], v[164:167], v[208:211], v[6:9]
	v_mfma_f32_16x16x32_bf16 v[2:5], v[168:171], v[208:211], v[2:5]
	s_waitcnt lgkmcnt(0)
	s_add_i32 s4, s14, 0xc0
	s_min_u32 s4, s4, 0x3c0
	s_lshl_b32 s4, s4, 1
	v_mfma_f32_16x16x32_bf16 v[94:97], v[212:215], v[216:219], v[94:97]
	v_mfma_f32_16x16x32_bf16 v[90:93], v[220:223], v[216:219], v[90:93]
	v_mfma_f32_16x16x32_bf16 v[86:89], v[224:227], v[216:219], v[86:89]
	v_mfma_f32_16x16x32_bf16 v[82:85], v[228:231], v[216:219], v[82:85]
	s_setprio 0
	s_barrier
	s_setprio 1
	v_mfma_f32_16x16x32_bf16 v[78:81], v[212:215], v[232:235], v[78:81]
	s_add_u32 m0, s15, 0x8000
	v_lshl_add_u64 v[200:201], v[184:185], 0, s[4:5]
	global_load_lds_dwordx4 v[200:201], off
	v_mfma_f32_16x16x32_bf16 v[74:77], v[220:223], v[232:235], v[74:77]
	v_mfma_f32_16x16x32_bf16 v[62:65], v[224:227], v[232:235], v[62:65]
	s_add_u32 m0, s15, 0x9000
	v_lshl_add_u64 v[202:203], v[186:187], 0, s[4:5]
	global_load_lds_dwordx4 v[202:203], off
	v_mfma_f32_16x16x32_bf16 v[30:33], v[228:231], v[232:235], v[30:33]
	v_mfma_f32_16x16x32_bf16 v[66:69], v[212:215], v[236:239], v[66:69]
	s_add_u32 m0, s15, 0xa000
	v_lshl_add_u64 v[200:201], v[188:189], 0, s[4:5]
	global_load_lds_dwordx4 v[200:201], off
	v_mfma_f32_16x16x32_bf16 v[38:41], v[220:223], v[236:239], v[38:41]
	v_mfma_f32_16x16x32_bf16 v[34:37], v[224:227], v[236:239], v[34:37]
	s_add_u32 m0, s15, 0xb000
	v_lshl_add_u64 v[202:203], v[190:191], 0, s[4:5]
	global_load_lds_dwordx4 v[202:203], off
	v_mfma_f32_16x16x32_bf16 v[18:21], v[228:231], v[236:239], v[18:21]
	v_mfma_f32_16x16x32_bf16 v[14:17], v[212:215], v[240:243], v[14:17]
	s_add_u32 m0, s15, 0xc000
	v_lshl_add_u64 v[200:201], v[192:193], 0, s[4:5]
	global_load_lds_dwordx4 v[200:201], off
	v_mfma_f32_16x16x32_bf16 v[10:13], v[220:223], v[240:243], v[10:13]
	s_add_u32 m0, s15, 0xd000
	v_lshl_add_u64 v[202:203], v[194:195], 0, s[4:5]
	global_load_lds_dwordx4 v[202:203], off
	v_mfma_f32_16x16x32_bf16 v[6:9], v[224:227], v[240:243], v[6:9]
	s_add_u32 m0, s15, 0xe000
	v_lshl_add_u64 v[200:201], v[196:197], 0, s[4:5]
	global_load_lds_dwordx4 v[200:201], off
	v_mfma_f32_16x16x32_bf16 v[2:5], v[228:231], v[240:243], v[2:5]
	s_add_u32 m0, s15, 0xf000
	v_lshl_add_u64 v[202:203], v[198:199], 0, s[4:5]
	global_load_lds_dwordx4 v[202:203], off
	s_setprio 0
	s_waitcnt vmcnt(8)
	s_barrier
	s_add_i32 s14, s14, 0x80
	s_add_i32 s13, s13, 2
	s_cmp_lt_u32 s13, 14
	s_cbranch_scc1 .Lglds2_12468
	s_waitcnt vmcnt(0)
	s_waitcnt vmcnt(0)
	v_or_b32_e32 v170, s12, v119
	v_add_lshl_u32 v98, v118, s11, 10
	v_readlane_b32 s12, v254, 8
	v_readlane_b32 s13, v254, 9
	v_readlane_b32 s14, v254, 10
	v_readlane_b32 s15, v254, 11
	v_readlane_b32 s16, v254, 12
	v_readlane_b32 s17, v254, 13
	v_readlane_b32 s18, v254, 14
	v_readlane_b32 s19, v254, 15
	v_readlane_b32 s20, v254, 16
	v_readlane_b32 s21, v254, 17
	v_readlane_b32 s22, v254, 18
	v_readlane_b32 s23, v254, 19
	v_readlane_b32 s24, v254, 20
	v_readlane_b32 s25, v254, 21
	v_readlane_b32 s26, v254, 22
	v_readlane_b32 s27, v254, 23
	v_lshlrev_b32_e32 v168, 2, v170
	v_mov_b32_e32 v169, v99
	v_lshlrev_b64 v[174:175], 2, v[98:99]
	v_lshl_add_u64 v[152:153], s[12:13], 0, v[174:175]
	v_lshl_add_u64 v[160:161], s[82:83], 0, v[174:175]
	v_lshl_add_u64 v[152:153], v[152:153], 0, v[168:169]
	v_lshl_add_u64 v[160:161], v[160:161], 0, v[168:169]
	global_load_dwordx4 v[120:123], v[152:153], off
	global_load_dwordx4 v[124:127], v[152:153], off offset:64
	global_load_dwordx4 v[128:131], v[152:153], off offset:128
	global_load_dwordx4 v[132:135], v[152:153], off offset:192
	v_or_b32_e32 v172, 0x4000, v98
	v_mov_b32_e32 v173, v99
	v_lshlrev_b64 v[174:175], 2, v[172:173]
	v_lshl_add_u64 v[154:155], s[12:13], 0, v[174:175]
	v_lshl_add_u64 v[162:163], s[82:83], 0, v[174:175]
	v_lshl_add_u64 v[154:155], v[154:155], 0, v[168:169]
	v_lshl_add_u64 v[162:163], v[162:163], 0, v[168:169]
	global_load_dwordx4 v[136:139], v[154:155], off
	global_load_dwordx4 v[140:143], v[154:155], off offset:64
	global_load_dwordx4 v[144:147], v[154:155], off offset:128
	global_load_dwordx4 v[148:151], v[154:155], off offset:192
	v_or_b32_e32 v172, 0x8000, v98
	v_mov_b32_e32 v173, v99
	v_lshlrev_b64 v[174:175], 2, v[172:173]
	v_lshl_add_u64 v[156:157], s[12:13], 0, v[174:175]
	v_lshl_add_u64 v[164:165], s[82:83], 0, v[174:175]
	v_lshl_add_u64 v[156:157], v[156:157], 0, v[168:169]
	v_lshl_add_u64 v[164:165], v[164:165], 0, v[168:169]
	global_load_dwordx4 v[22:25], v[156:157], off
	global_load_dwordx4 v[26:29], v[156:157], off offset:64
	global_load_dwordx4 v[42:45], v[156:157], off offset:128
	global_load_dwordx4 v[46:49], v[156:157], off offset:192
	v_or_b32_e32 v172, 0xc000, v98
	v_mov_b32_e32 v173, v99
	v_lshlrev_b64 v[174:175], 2, v[172:173]
	v_lshl_add_u64 v[158:159], s[12:13], 0, v[174:175]
	v_lshl_add_u64 v[166:167], s[82:83], 0, v[174:175]
	v_lshl_add_u64 v[158:159], v[158:159], 0, v[168:169]
	v_lshl_add_u64 v[166:167], v[166:167], 0, v[168:169]
	global_load_dwordx4 v[50:53], v[158:159], off
	global_load_dwordx4 v[54:57], v[158:159], off offset:64
	global_load_dwordx4 v[58:61], v[158:159], off offset:128
	global_load_dwordx4 v[70:73], v[158:159], off offset:192
	s_waitcnt vmcnt(15)
	v_pk_fma_f32 v[120:121], v[120:121], s[6:7], v[94:95] op_sel_hi:[1,0,1]
	v_pk_fma_f32 v[122:123], v[122:123], s[6:7], v[96:97] op_sel_hi:[1,0,1]
	s_waitcnt vmcnt(14)
	v_pk_fma_f32 v[124:125], v[124:125], s[6:7], v[90:91] op_sel_hi:[1,0,1]
	v_pk_fma_f32 v[126:127], v[126:127], s[6:7], v[92:93] op_sel_hi:[1,0,1]
	s_waitcnt vmcnt(13)
	v_pk_fma_f32 v[128:129], v[128:129], s[6:7], v[86:87] op_sel_hi:[1,0,1]
	v_pk_fma_f32 v[130:131], v[130:131], s[6:7], v[88:89] op_sel_hi:[1,0,1]
	s_waitcnt vmcnt(12)
	v_pk_fma_f32 v[132:133], v[132:133], s[6:7], v[82:83] op_sel_hi:[1,0,1]
	v_pk_fma_f32 v[134:135], v[134:135], s[6:7], v[84:85] op_sel_hi:[1,0,1]
	s_waitcnt vmcnt(11)
	v_pk_fma_f32 v[136:137], v[136:137], s[6:7], v[78:79] op_sel_hi:[1,0,1]
	v_pk_fma_f32 v[138:139], v[138:139], s[6:7], v[80:81] op_sel_hi:[1,0,1]
	s_waitcnt vmcnt(10)
	v_pk_fma_f32 v[140:141], v[140:141], s[6:7], v[74:75] op_sel_hi:[1,0,1]
	v_pk_fma_f32 v[142:143], v[142:143], s[6:7], v[76:77] op_sel_hi:[1,0,1]
	s_waitcnt vmcnt(9)
	v_pk_fma_f32 v[144:145], v[144:145], s[6:7], v[62:63] op_sel_hi:[1,0,1]
	v_pk_fma_f32 v[146:147], v[146:147], s[6:7], v[64:65] op_sel_hi:[1,0,1]
	s_waitcnt vmcnt(8)
	v_pk_fma_f32 v[148:149], v[148:149], s[6:7], v[30:31] op_sel_hi:[1,0,1]
	v_pk_fma_f32 v[150:151], v[150:151], s[6:7], v[32:33] op_sel_hi:[1,0,1]
	s_waitcnt vmcnt(7)
	v_pk_fma_f32 v[22:23], v[22:23], s[6:7], v[66:67] op_sel_hi:[1,0,1]
	v_pk_fma_f32 v[24:25], v[24:25], s[6:7], v[68:69] op_sel_hi:[1,0,1]
	s_waitcnt vmcnt(6)
	v_pk_fma_f32 v[26:27], v[26:27], s[6:7], v[38:39] op_sel_hi:[1,0,1]
	v_pk_fma_f32 v[28:29], v[28:29], s[6:7], v[40:41] op_sel_hi:[1,0,1]
	s_waitcnt vmcnt(5)
	v_pk_fma_f32 v[42:43], v[42:43], s[6:7], v[34:35] op_sel_hi:[1,0,1]
	v_pk_fma_f32 v[44:45], v[44:45], s[6:7], v[36:37] op_sel_hi:[1,0,1]
	s_waitcnt vmcnt(4)
	v_pk_fma_f32 v[46:47], v[46:47], s[6:7], v[18:19] op_sel_hi:[1,0,1]
	v_pk_fma_f32 v[48:49], v[48:49], s[6:7], v[20:21] op_sel_hi:[1,0,1]
	s_waitcnt vmcnt(3)
	v_pk_fma_f32 v[50:51], v[50:51], s[6:7], v[14:15] op_sel_hi:[1,0,1]
	v_pk_fma_f32 v[52:53], v[52:53], s[6:7], v[16:17] op_sel_hi:[1,0,1]
	s_waitcnt vmcnt(2)
	v_pk_fma_f32 v[54:55], v[54:55], s[6:7], v[10:11] op_sel_hi:[1,0,1]
	v_pk_fma_f32 v[56:57], v[56:57], s[6:7], v[12:13] op_sel_hi:[1,0,1]
	s_waitcnt vmcnt(1)
	v_pk_fma_f32 v[58:59], v[58:59], s[6:7], v[6:7] op_sel_hi:[1,0,1]
	v_pk_fma_f32 v[60:61], v[60:61], s[6:7], v[8:9] op_sel_hi:[1,0,1]
	s_waitcnt vmcnt(0)
	v_pk_fma_f32 v[70:71], v[70:71], s[6:7], v[2:3] op_sel_hi:[1,0,1]
	v_pk_fma_f32 v[72:73], v[72:73], s[6:7], v[4:5] op_sel_hi:[1,0,1]
	global_store_dwordx4 v[160:161], v[120:123], off
	global_store_dwordx4 v[160:161], v[124:127], off offset:64
	global_store_dwordx4 v[160:161], v[128:131], off offset:128
	global_store_dwordx4 v[160:161], v[132:135], off offset:192
	global_store_dwordx4 v[162:163], v[136:139], off
	global_store_dwordx4 v[162:163], v[140:143], off offset:64
	global_store_dwordx4 v[162:163], v[144:147], off offset:128
	global_store_dwordx4 v[162:163], v[148:151], off offset:192
	global_store_dwordx4 v[164:165], v[22:25], off
	global_store_dwordx4 v[164:165], v[26:29], off offset:64
	global_store_dwordx4 v[164:165], v[42:45], off offset:128
	global_store_dwordx4 v[164:165], v[46:49], off offset:192
	global_store_dwordx4 v[166:167], v[50:53], off
	global_store_dwordx4 v[166:167], v[54:57], off offset:64
	global_store_dwordx4 v[166:167], v[58:61], off offset:128
	global_store_dwordx4 v[166:167], v[70:73], off offset:192
	s_add_i32 s7, s7, s3
	s_cmpk_lt_u32 s7, 0x100
	s_cbranch_scc1 .LBB0_422

.Lglds2_14401:
	ds_read_b128 v[152:155], v112 offset:16384
	ds_read_b128 v[156:159], v110
	ds_read_b128 v[160:163], v112 offset:18432
	ds_read_b128 v[164:167], v112 offset:20480
	ds_read_b128 v[168:171], v113 offset:16384
	ds_read_b128 v[172:175], v110 offset:2048
	ds_read_b128 v[204:207], v110 offset:4096
	ds_read_b128 v[208:211], v111
	ds_read_b128 v[212:215], v116 offset:16384
	ds_read_b128 v[216:219], v114
	ds_read_b128 v[220:223], v116 offset:18432
	ds_read_b128 v[224:227], v116 offset:20480
	ds_read_b128 v[228:231], v117 offset:16384
	ds_read_b128 v[232:235], v114 offset:2048
	ds_read_b128 v[236:239], v114 offset:4096
	ds_read_b128 v[240:243], v115
	s_setprio 1
	s_waitcnt lgkmcnt(14)
	v_mfma_i32_16x16x64_i8 v[94:97], v[152:155], v[156:159], v[94:97]
	s_waitcnt lgkmcnt(13)
	v_mfma_i32_16x16x64_i8 v[90:93], v[160:163], v[156:159], v[90:93]
	s_waitcnt lgkmcnt(12)
	v_mfma_i32_16x16x64_i8 v[86:89], v[164:167], v[156:159], v[86:89]
	s_waitcnt lgkmcnt(11)
	v_mfma_i32_16x16x64_i8 v[82:85], v[168:171], v[156:159], v[82:85]
	s_waitcnt lgkmcnt(10)
	v_mfma_i32_16x16x64_i8 v[74:77], v[152:155], v[172:175], v[74:77]
	v_mfma_i32_16x16x64_i8 v[50:53], v[160:163], v[172:175], v[50:53]
	v_mfma_i32_16x16x64_i8 v[38:41], v[164:167], v[172:175], v[38:41]
	v_mfma_i32_16x16x64_i8 v[30:33], v[168:171], v[172:175], v[30:33]
	s_waitcnt lgkmcnt(9)
	v_mfma_i32_16x16x64_i8 v[34:37], v[152:155], v[204:207], v[34:37]
	v_mfma_i32_16x16x64_i8 v[26:29], v[160:163], v[204:207], v[26:29]
	v_mfma_i32_16x16x64_i8 v[22:25], v[164:167], v[204:207], v[22:25]
	v_mfma_i32_16x16x64_i8 v[18:21], v[168:171], v[204:207], v[18:21]
	s_waitcnt lgkmcnt(8)
	v_mfma_i32_16x16x64_i8 v[14:17], v[152:155], v[208:211], v[14:17]
	v_mfma_i32_16x16x64_i8 v[10:13], v[160:163], v[208:211], v[10:13]
	v_mfma_i32_16x16x64_i8 v[6:9], v[164:167], v[208:211], v[6:9]
	v_mfma_i32_16x16x64_i8 v[2:5], v[168:171], v[208:211], v[2:5]
	s_waitcnt lgkmcnt(0)
	s_add_i32 s4, s13, 0x80
	s_min_u32 s4, s4, 0x1c0
	s_lshl_b32 s4, s4, 1
	v_mfma_i32_16x16x64_i8 v[94:97], v[212:215], v[216:219], v[94:97]
	v_mfma_i32_16x16x64_i8 v[90:93], v[220:223], v[216:219], v[90:93]
	v_mfma_i32_16x16x64_i8 v[86:89], v[224:227], v[216:219], v[86:89]
	v_mfma_i32_16x16x64_i8 v[82:85], v[228:231], v[216:219], v[82:85]
	s_setprio 0
	s_barrier
	s_setprio 1
	v_mfma_i32_16x16x64_i8 v[74:77], v[212:215], v[232:235], v[74:77]
	s_add_u32 m0, s14, 0x0
	v_lshl_add_u64 v[200:201], v[184:185], 0, s[4:5]
	global_load_lds_dwordx4 v[200:201], off
	v_mfma_i32_16x16x64_i8 v[50:53], v[220:223], v[232:235], v[50:53]
	v_mfma_i32_16x16x64_i8 v[38:41], v[224:227], v[232:235], v[38:41]
	s_add_u32 m0, s14, 0x1000
	v_lshl_add_u64 v[202:203], v[186:187], 0, s[4:5]
	global_load_lds_dwordx4 v[202:203], off
	v_mfma_i32_16x16x64_i8 v[30:33], v[228:231], v[232:235], v[30:33]
	v_mfma_i32_16x16x64_i8 v[34:37], v[212:215], v[236:239], v[34:37]
	s_add_u32 m0, s14, 0x2000
	v_lshl_add_u64 v[200:201], v[188:189], 0, s[4:5]
	global_load_lds_dwordx4 v[200:201], off
	v_mfma_i32_16x16x64_i8 v[26:29], v[220:223], v[236:239], v[26:29]
	v_mfma_i32_16x16x64_i8 v[22:25], v[224:227], v[236:239], v[22:25]
	s_add_u32 m0, s14, 0x3000
	v_lshl_add_u64 v[202:203], v[190:191], 0, s[4:5]
	global_load_lds_dwordx4 v[202:203], off
	v_mfma_i32_16x16x64_i8 v[18:21], v[228:231], v[236:239], v[18:21]
	v_mfma_i32_16x16x64_i8 v[14:17], v[212:215], v[240:243], v[14:17]
	s_add_u32 m0, s14, 0x4000
	v_lshl_add_u64 v[200:201], v[192:193], 0, s[4:5]
	global_load_lds_dwordx4 v[200:201], off
	v_mfma_i32_16x16x64_i8 v[10:13], v[220:223], v[240:243], v[10:13]
	s_add_u32 m0, s14, 0x5000
	v_lshl_add_u64 v[202:203], v[194:195], 0, s[4:5]
	global_load_lds_dwordx4 v[202:203], off
	v_mfma_i32_16x16x64_i8 v[6:9], v[224:227], v[240:243], v[6:9]
	s_add_u32 m0, s14, 0x6000
	v_lshl_add_u64 v[200:201], v[196:197], 0, s[4:5]
	global_load_lds_dwordx4 v[200:201], off
	v_mfma_i32_16x16x64_i8 v[2:5], v[228:231], v[240:243], v[2:5]
	s_add_u32 m0, s14, 0x7000
	v_lshl_add_u64 v[202:203], v[198:199], 0, s[4:5]
	global_load_lds_dwordx4 v[202:203], off
	s_setprio 0
	s_waitcnt vmcnt(8)
	s_barrier
	ds_read_b128 v[152:155], v112 offset:49152
	ds_read_b128 v[156:159], v110 offset:32768
	ds_read_b128 v[160:163], v112 offset:51200
	ds_read_b128 v[164:167], v112 offset:53248
	ds_read_b128 v[168:171], v113 offset:49152
	ds_read_b128 v[172:175], v110 offset:34816
	ds_read_b128 v[204:207], v110 offset:36864
	ds_read_b128 v[208:211], v111 offset:32768
	ds_read_b128 v[212:215], v116 offset:49152
	ds_read_b128 v[216:219], v114 offset:32768
	ds_read_b128 v[220:223], v116 offset:51200
	ds_read_b128 v[224:227], v116 offset:53248
	ds_read_b128 v[228:231], v117 offset:49152
	ds_read_b128 v[232:235], v114 offset:34816
	ds_read_b128 v[236:239], v114 offset:36864
	ds_read_b128 v[240:243], v115 offset:32768
	s_setprio 1
	s_waitcnt lgkmcnt(14)
	v_mfma_i32_16x16x64_i8 v[94:97], v[152:155], v[156:159], v[94:97]
	s_waitcnt lgkmcnt(13)
	v_mfma_i32_16x16x64_i8 v[90:93], v[160:163], v[156:159], v[90:93]
	s_waitcnt lgkmcnt(12)
	v_mfma_i32_16x16x64_i8 v[86:89], v[164:167], v[156:159], v[86:89]
	s_waitcnt lgkmcnt(11)
	v_mfma_i32_16x16x64_i8 v[82:85], v[168:171], v[156:159], v[82:85]
	s_waitcnt lgkmcnt(10)
	v_mfma_i32_16x16x64_i8 v[74:77], v[152:155], v[172:175], v[74:77]
	v_mfma_i32_16x16x64_i8 v[50:53], v[160:163], v[172:175], v[50:53]
	v_mfma_i32_16x16x64_i8 v[38:41], v[164:167], v[172:175], v[38:41]
	v_mfma_i32_16x16x64_i8 v[30:33], v[168:171], v[172:175], v[30:33]
	s_waitcnt lgkmcnt(9)
	v_mfma_i32_16x16x64_i8 v[34:37], v[152:155], v[204:207], v[34:37]
	v_mfma_i32_16x16x64_i8 v[26:29], v[160:163], v[204:207], v[26:29]
	v_mfma_i32_16x16x64_i8 v[22:25], v[164:167], v[204:207], v[22:25]
	v_mfma_i32_16x16x64_i8 v[18:21], v[168:171], v[204:207], v[18:21]
	s_waitcnt lgkmcnt(8)
	v_mfma_i32_16x16x64_i8 v[14:17], v[152:155], v[208:211], v[14:17]
	v_mfma_i32_16x16x64_i8 v[10:13], v[160:163], v[208:211], v[10:13]
	v_mfma_i32_16x16x64_i8 v[6:9], v[164:167], v[208:211], v[6:9]
	v_mfma_i32_16x16x64_i8 v[2:5], v[168:171], v[208:211], v[2:5]
	s_waitcnt lgkmcnt(0)
	s_add_i32 s4, s13, 0xc0
	s_min_u32 s4, s4, 0x1c0
	s_lshl_b32 s4, s4, 1
	v_mfma_i32_16x16x64_i8 v[94:97], v[212:215], v[216:219], v[94:97]
	v_mfma_i32_16x16x64_i8 v[90:93], v[220:223], v[216:219], v[90:93]
	v_mfma_i32_16x16x64_i8 v[86:89], v[224:227], v[216:219], v[86:89]
	v_mfma_i32_16x16x64_i8 v[82:85], v[228:231], v[216:219], v[82:85]
	s_setprio 0
	s_barrier
	s_setprio 1
	v_mfma_i32_16x16x64_i8 v[74:77], v[212:215], v[232:235], v[74:77]
	s_add_u32 m0, s14, 0x8000
	v_lshl_add_u64 v[200:201], v[184:185], 0, s[4:5]
	global_load_lds_dwordx4 v[200:201], off
	v_mfma_i32_16x16x64_i8 v[50:53], v[220:223], v[232:235], v[50:53]
	v_mfma_i32_16x16x64_i8 v[38:41], v[224:227], v[232:235], v[38:41]
	s_add_u32 m0, s14, 0x9000
	v_lshl_add_u64 v[202:203], v[186:187], 0, s[4:5]
	global_load_lds_dwordx4 v[202:203], off
	v_mfma_i32_16x16x64_i8 v[30:33], v[228:231], v[232:235], v[30:33]
	v_mfma_i32_16x16x64_i8 v[34:37], v[212:215], v[236:239], v[34:37]
	s_add_u32 m0, s14, 0xa000
	v_lshl_add_u64 v[200:201], v[188:189], 0, s[4:5]
	global_load_lds_dwordx4 v[200:201], off
	v_mfma_i32_16x16x64_i8 v[26:29], v[220:223], v[236:239], v[26:29]
	v_mfma_i32_16x16x64_i8 v[22:25], v[224:227], v[236:239], v[22:25]
	s_add_u32 m0, s14, 0xb000
	v_lshl_add_u64 v[202:203], v[190:191], 0, s[4:5]
	global_load_lds_dwordx4 v[202:203], off
	v_mfma_i32_16x16x64_i8 v[18:21], v[228:231], v[236:239], v[18:21]
	v_mfma_i32_16x16x64_i8 v[14:17], v[212:215], v[240:243], v[14:17]
	s_add_u32 m0, s14, 0xc000
	v_lshl_add_u64 v[200:201], v[192:193], 0, s[4:5]
	global_load_lds_dwordx4 v[200:201], off
	v_mfma_i32_16x16x64_i8 v[10:13], v[220:223], v[240:243], v[10:13]
	s_add_u32 m0, s14, 0xd000
	v_lshl_add_u64 v[202:203], v[194:195], 0, s[4:5]
	global_load_lds_dwordx4 v[202:203], off
	v_mfma_i32_16x16x64_i8 v[6:9], v[224:227], v[240:243], v[6:9]
	s_add_u32 m0, s14, 0xe000
	v_lshl_add_u64 v[200:201], v[196:197], 0, s[4:5]
	global_load_lds_dwordx4 v[200:201], off
	v_mfma_i32_16x16x64_i8 v[2:5], v[228:231], v[240:243], v[2:5]
	s_add_u32 m0, s14, 0xf000
	v_lshl_add_u64 v[202:203], v[198:199], 0, s[4:5]
	global_load_lds_dwordx4 v[202:203], off
	s_setprio 0
	s_waitcnt vmcnt(8)
	s_barrier
	s_add_i32 s13, s13, 0x80
	s_add_i32 s12, s12, 2
	s_cmp_lt_u32 s12, 6
	s_cbranch_scc1 .Lglds2_14401
	s_waitcnt vmcnt(0)
	v_cvt_f32_i32_e32 v94, v94
	v_cvt_f32_i32_e32 v95, v95
	v_cvt_f32_i32_e32 v96, v96
	v_cvt_f32_i32_e32 v97, v97
	v_cvt_f32_i32_e32 v90, v90
	v_cvt_f32_i32_e32 v91, v91
	v_cvt_f32_i32_e32 v92, v92
	v_cvt_f32_i32_e32 v93, v93
	v_cvt_f32_i32_e32 v86, v86
	v_cvt_f32_i32_e32 v87, v87
	v_cvt_f32_i32_e32 v88, v88
	v_cvt_f32_i32_e32 v89, v89
	v_cvt_f32_i32_e32 v82, v82
	v_cvt_f32_i32_e32 v83, v83
	v_cvt_f32_i32_e32 v84, v84
	v_cvt_f32_i32_e32 v85, v85
	v_cvt_f32_i32_e32 v74, v74
	v_cvt_f32_i32_e32 v75, v75
	v_cvt_f32_i32_e32 v76, v76
	v_cvt_f32_i32_e32 v77, v77
	v_cvt_f32_i32_e32 v50, v50
	v_cvt_f32_i32_e32 v51, v51
	v_cvt_f32_i32_e32 v52, v52
	v_cvt_f32_i32_e32 v53, v53
	v_cvt_f32_i32_e32 v38, v38
	v_cvt_f32_i32_e32 v39, v39
	v_cvt_f32_i32_e32 v40, v40
	v_cvt_f32_i32_e32 v41, v41
	v_cvt_f32_i32_e32 v30, v30
	v_cvt_f32_i32_e32 v31, v31
	v_cvt_f32_i32_e32 v32, v32
	v_cvt_f32_i32_e32 v33, v33
	v_cvt_f32_i32_e32 v34, v34
	v_cvt_f32_i32_e32 v35, v35
	v_cvt_f32_i32_e32 v36, v36
	v_cvt_f32_i32_e32 v37, v37
	v_cvt_f32_i32_e32 v26, v26
	v_cvt_f32_i32_e32 v27, v27
	v_cvt_f32_i32_e32 v28, v28
	v_cvt_f32_i32_e32 v29, v29
	v_cvt_f32_i32_e32 v22, v22
	v_cvt_f32_i32_e32 v23, v23
	v_cvt_f32_i32_e32 v24, v24
	v_cvt_f32_i32_e32 v25, v25
	v_cvt_f32_i32_e32 v18, v18
	v_cvt_f32_i32_e32 v19, v19
	v_cvt_f32_i32_e32 v20, v20
	v_cvt_f32_i32_e32 v21, v21
	v_cvt_f32_i32_e32 v14, v14
	v_cvt_f32_i32_e32 v15, v15
	v_cvt_f32_i32_e32 v16, v16
	v_cvt_f32_i32_e32 v17, v17
	v_cvt_f32_i32_e32 v10, v10
	v_cvt_f32_i32_e32 v11, v11
	v_cvt_f32_i32_e32 v12, v12
	v_cvt_f32_i32_e32 v13, v13
	v_cvt_f32_i32_e32 v6, v6
	v_cvt_f32_i32_e32 v7, v7
	v_cvt_f32_i32_e32 v8, v8
	v_cvt_f32_i32_e32 v9, v9
	v_cvt_f32_i32_e32 v2, v2
	v_cvt_f32_i32_e32 v3, v3
	v_cvt_f32_i32_e32 v4, v4
	v_cvt_f32_i32_e32 v5, v5
	s_waitcnt vmcnt(0)
	v_add_u32_e32 v98, s10, v118
	v_or_b32_e32 v146, s11, v119
	v_lshl_add_u64 v[144:145], v[98:99], 2, s[68:69]
	v_lshlrev_b32_e32 v148, 2, v146
	global_load_dword v136, v[144:145], off
	global_load_dword v138, v[144:145], off offset:64
	global_load_dword v140, v[144:145], off offset:128
	global_load_dword v142, v[144:145], off offset:192
	global_load_dwordx4 v[120:123], v148, s[74:75]
	global_load_dwordx4 v[124:127], v148, s[74:75] offset:64
	global_load_dwordx4 v[128:131], v148, s[74:75] offset:128
	global_load_dwordx4 v[132:135], v148, s[74:75] offset:192
	v_lshlrev_b32_e32 v146, 1, v146
	v_mov_b32_e32 v147, v99
	v_lshlrev_b64 v[42:43], 12, v[98:99]
	v_lshl_add_u64 v[42:43], s[64:65], 0, v[42:43]
	v_lshl_add_u64 v[42:43], v[42:43], 0, v[146:147]
	v_or_b32_e32 v54, 16, v98
	v_mov_b32_e32 v55, v99
	v_lshlrev_b64 v[44:45], 12, v[54:55]
	v_lshl_add_u64 v[44:45], s[64:65], 0, v[44:45]
	v_lshl_add_u64 v[44:45], v[44:45], 0, v[146:147]
	v_or_b32_e32 v54, 32, v98
	v_mov_b32_e32 v55, v99
	v_lshlrev_b64 v[46:47], 12, v[54:55]
	v_lshl_add_u64 v[46:47], s[64:65], 0, v[46:47]
	v_lshl_add_u64 v[46:47], v[46:47], 0, v[146:147]
	v_or_b32_e32 v54, 48, v98
	v_mov_b32_e32 v55, v99
	v_lshlrev_b64 v[48:49], 12, v[54:55]
	v_lshl_add_u64 v[48:49], s[64:65], 0, v[48:49]
	v_lshl_add_u64 v[48:49], v[48:49], 0, v[146:147]
	s_waitcnt vmcnt(0)
	v_pk_mul_f32 v[94:95], v[136:137], v[94:95] op_sel_hi:[0,1]
	v_pk_mul_f32 v[96:97], v[136:137], v[96:97] op_sel_hi:[0,1]
	v_pk_mul_f32 v[94:95], v[120:121], v[94:95]
	v_pk_mul_f32 v[96:97], v[96:97], v[122:123]
	v_cvt_pk_bf16_f32 v94, v94, v95
	v_cvt_pk_bf16_f32 v95, v96, v97
	global_store_dwordx2 v[42:43], v[94:95], off
	v_pk_mul_f32 v[90:91], v[136:137], v[90:91] op_sel_hi:[0,1]
	v_pk_mul_f32 v[92:93], v[136:137], v[92:93] op_sel_hi:[0,1]
	v_pk_mul_f32 v[90:91], v[124:125], v[90:91]
	v_pk_mul_f32 v[92:93], v[92:93], v[126:127]
	v_cvt_pk_bf16_f32 v90, v90, v91
	v_cvt_pk_bf16_f32 v91, v92, v93
	global_store_dwordx2 v[42:43], v[90:91], off offset:32
	v_pk_mul_f32 v[86:87], v[136:137], v[86:87] op_sel_hi:[0,1]
	v_pk_mul_f32 v[88:89], v[136:137], v[88:89] op_sel_hi:[0,1]
	v_pk_mul_f32 v[86:87], v[128:129], v[86:87]
	v_pk_mul_f32 v[88:89], v[88:89], v[130:131]
	v_cvt_pk_bf16_f32 v86, v86, v87
	v_cvt_pk_bf16_f32 v87, v88, v89
	global_store_dwordx2 v[42:43], v[86:87], off offset:64
	v_pk_mul_f32 v[82:83], v[136:137], v[82:83] op_sel_hi:[0,1]
	v_pk_mul_f32 v[84:85], v[136:137], v[84:85] op_sel_hi:[0,1]
	v_pk_mul_f32 v[82:83], v[132:133], v[82:83]
	v_pk_mul_f32 v[84:85], v[84:85], v[134:135]
	v_cvt_pk_bf16_f32 v82, v82, v83
	v_cvt_pk_bf16_f32 v83, v84, v85
	global_store_dwordx2 v[42:43], v[82:83], off offset:96
	v_pk_mul_f32 v[74:75], v[138:139], v[74:75] op_sel_hi:[0,1]
	v_pk_mul_f32 v[76:77], v[138:139], v[76:77] op_sel_hi:[0,1]
	v_pk_mul_f32 v[74:75], v[120:121], v[74:75]
	v_pk_mul_f32 v[76:77], v[76:77], v[122:123]
	v_cvt_pk_bf16_f32 v74, v74, v75
	v_cvt_pk_bf16_f32 v75, v76, v77
	global_store_dwordx2 v[44:45], v[74:75], off
	v_pk_mul_f32 v[50:51], v[138:139], v[50:51] op_sel_hi:[0,1]
	v_pk_mul_f32 v[52:53], v[138:139], v[52:53] op_sel_hi:[0,1]
	v_pk_mul_f32 v[50:51], v[124:125], v[50:51]
	v_pk_mul_f32 v[52:53], v[52:53], v[126:127]
	v_cvt_pk_bf16_f32 v50, v50, v51
	v_cvt_pk_bf16_f32 v51, v52, v53
	global_store_dwordx2 v[44:45], v[50:51], off offset:32
	v_pk_mul_f32 v[38:39], v[138:139], v[38:39] op_sel_hi:[0,1]
	v_pk_mul_f32 v[40:41], v[138:139], v[40:41] op_sel_hi:[0,1]
	v_pk_mul_f32 v[38:39], v[128:129], v[38:39]
	v_pk_mul_f32 v[40:41], v[40:41], v[130:131]
	v_cvt_pk_bf16_f32 v38, v38, v39
	v_cvt_pk_bf16_f32 v39, v40, v41
	global_store_dwordx2 v[44:45], v[38:39], off offset:64
	v_pk_mul_f32 v[30:31], v[138:139], v[30:31] op_sel_hi:[0,1]
	v_pk_mul_f32 v[32:33], v[138:139], v[32:33] op_sel_hi:[0,1]
	v_pk_mul_f32 v[30:31], v[132:133], v[30:31]
	v_pk_mul_f32 v[32:33], v[32:33], v[134:135]
	v_cvt_pk_bf16_f32 v30, v30, v31
	v_cvt_pk_bf16_f32 v31, v32, v33
	global_store_dwordx2 v[44:45], v[30:31], off offset:96
	v_pk_mul_f32 v[34:35], v[140:141], v[34:35] op_sel_hi:[0,1]
	v_pk_mul_f32 v[36:37], v[140:141], v[36:37] op_sel_hi:[0,1]
	v_pk_mul_f32 v[34:35], v[120:121], v[34:35]
	v_pk_mul_f32 v[36:37], v[36:37], v[122:123]
	v_cvt_pk_bf16_f32 v34, v34, v35
	v_cvt_pk_bf16_f32 v35, v36, v37
	global_store_dwordx2 v[46:47], v[34:35], off
	v_pk_mul_f32 v[26:27], v[140:141], v[26:27] op_sel_hi:[0,1]
	v_pk_mul_f32 v[28:29], v[140:141], v[28:29] op_sel_hi:[0,1]
	v_pk_mul_f32 v[26:27], v[124:125], v[26:27]
	v_pk_mul_f32 v[28:29], v[28:29], v[126:127]
	v_cvt_pk_bf16_f32 v26, v26, v27
	v_cvt_pk_bf16_f32 v27, v28, v29
	global_store_dwordx2 v[46:47], v[26:27], off offset:32
	v_pk_mul_f32 v[22:23], v[140:141], v[22:23] op_sel_hi:[0,1]
	v_pk_mul_f32 v[24:25], v[140:141], v[24:25] op_sel_hi:[0,1]
	v_pk_mul_f32 v[22:23], v[128:129], v[22:23]
	v_pk_mul_f32 v[24:25], v[24:25], v[130:131]
	v_cvt_pk_bf16_f32 v22, v22, v23
	v_cvt_pk_bf16_f32 v23, v24, v25
	global_store_dwordx2 v[46:47], v[22:23], off offset:64
	v_pk_mul_f32 v[18:19], v[140:141], v[18:19] op_sel_hi:[0,1]
	v_pk_mul_f32 v[20:21], v[140:141], v[20:21] op_sel_hi:[0,1]
	v_pk_mul_f32 v[18:19], v[132:133], v[18:19]
	v_pk_mul_f32 v[20:21], v[20:21], v[134:135]
	v_cvt_pk_bf16_f32 v18, v18, v19
	v_cvt_pk_bf16_f32 v19, v20, v21
	global_store_dwordx2 v[46:47], v[18:19], off offset:96
	v_pk_mul_f32 v[14:15], v[142:143], v[14:15] op_sel_hi:[0,1]
	v_pk_mul_f32 v[16:17], v[142:143], v[16:17] op_sel_hi:[0,1]
	v_pk_mul_f32 v[14:15], v[120:121], v[14:15]
	v_pk_mul_f32 v[16:17], v[16:17], v[122:123]
	v_cvt_pk_bf16_f32 v14, v14, v15
	v_cvt_pk_bf16_f32 v15, v16, v17
	global_store_dwordx2 v[48:49], v[14:15], off
	v_pk_mul_f32 v[10:11], v[142:143], v[10:11] op_sel_hi:[0,1]
	v_pk_mul_f32 v[12:13], v[142:143], v[12:13] op_sel_hi:[0,1]
	v_pk_mul_f32 v[10:11], v[124:125], v[10:11]
	v_pk_mul_f32 v[12:13], v[12:13], v[126:127]
	v_cvt_pk_bf16_f32 v10, v10, v11
	v_cvt_pk_bf16_f32 v11, v12, v13
	global_store_dwordx2 v[48:49], v[10:11], off offset:32
	v_pk_mul_f32 v[6:7], v[142:143], v[6:7] op_sel_hi:[0,1]
	v_pk_mul_f32 v[8:9], v[142:143], v[8:9] op_sel_hi:[0,1]
	v_pk_mul_f32 v[6:7], v[128:129], v[6:7]
	v_pk_mul_f32 v[8:9], v[8:9], v[130:131]
	v_cvt_pk_bf16_f32 v6, v6, v7
	v_cvt_pk_bf16_f32 v7, v8, v9
	global_store_dwordx2 v[48:49], v[6:7], off offset:64
	v_pk_mul_f32 v[2:3], v[142:143], v[2:3] op_sel_hi:[0,1]
	v_pk_mul_f32 v[4:5], v[142:143], v[4:5] op_sel_hi:[0,1]
	v_pk_mul_f32 v[2:3], v[132:133], v[2:3]
	v_pk_mul_f32 v[4:5], v[4:5], v[134:135]
	v_cvt_pk_bf16_f32 v2, v2, v3
	v_cvt_pk_bf16_f32 v3, v4, v5
	global_store_dwordx2 v[48:49], v[2:3], off offset:96
	s_add_i32 s6, s6, s3
	s_cmpk_lt_u32 s6, 0x200
	s_cbranch_scc1 .LBB0_518

.Lglds2_22142:
	ds_read_b128 v[152:155], v112 offset:16384
	ds_read_b128 v[156:159], v110
	ds_read_b128 v[160:163], v112 offset:18432
	ds_read_b128 v[164:167], v112 offset:20480
	ds_read_b128 v[168:171], v113 offset:16384
	ds_read_b128 v[172:175], v110 offset:2048
	ds_read_b128 v[208:211], v110 offset:4096
	ds_read_b128 v[212:215], v111
	ds_read_b128 v[216:219], v116 offset:16384
	ds_read_b128 v[220:223], v114
	ds_read_b128 v[224:227], v116 offset:18432
	ds_read_b128 v[228:231], v116 offset:20480
	ds_read_b128 v[232:235], v117 offset:16384
	ds_read_b128 v[236:239], v114 offset:2048
	ds_read_b128 v[240:243], v114 offset:4096
	ds_read_b128 v[244:247], v115
	s_setprio 1
	s_waitcnt lgkmcnt(14)
	v_mfma_f32_16x16x32_bf16 v[94:97], v[152:155], v[156:159], v[94:97]
	s_waitcnt lgkmcnt(13)
	v_mfma_f32_16x16x32_bf16 v[90:93], v[160:163], v[156:159], v[90:93]
	s_waitcnt lgkmcnt(12)
	v_mfma_f32_16x16x32_bf16 v[86:89], v[164:167], v[156:159], v[86:89]
	s_waitcnt lgkmcnt(11)
	v_mfma_f32_16x16x32_bf16 v[82:85], v[168:171], v[156:159], v[82:85]
	s_waitcnt lgkmcnt(10)
	v_mfma_f32_16x16x32_bf16 v[54:57], v[152:155], v[172:175], v[54:57]
	v_mfma_f32_16x16x32_bf16 v[42:45], v[160:163], v[172:175], v[42:45]
	v_mfma_f32_16x16x32_bf16 v[38:41], v[164:167], v[172:175], v[38:41]
	v_mfma_f32_16x16x32_bf16 v[34:37], v[168:171], v[172:175], v[34:37]
	s_waitcnt lgkmcnt(9)
	v_mfma_f32_16x16x32_bf16 v[78:81], v[152:155], v[208:211], v[78:81]
	v_mfma_f32_16x16x32_bf16 v[74:77], v[160:163], v[208:211], v[74:77]
	v_mfma_f32_16x16x32_bf16 v[70:73], v[164:167], v[208:211], v[70:73]
	v_mfma_f32_16x16x32_bf16 v[66:69], v[168:171], v[208:211], v[66:69]
	s_waitcnt lgkmcnt(8)
	v_mfma_f32_16x16x32_bf16 v[62:65], v[152:155], v[212:215], v[62:65]
	v_mfma_f32_16x16x32_bf16 v[58:61], v[160:163], v[212:215], v[58:61]
	v_mfma_f32_16x16x32_bf16 v[50:53], v[164:167], v[212:215], v[50:53]
	v_mfma_f32_16x16x32_bf16 v[46:49], v[168:171], v[212:215], v[46:49]
	s_waitcnt lgkmcnt(0)
	s_add_i32 s4, s16, 0x80
	s_min_u32 s4, s4, 0x3c0
	s_lshl_b32 s4, s4, 1
	v_mfma_f32_16x16x32_bf16 v[94:97], v[216:219], v[220:223], v[94:97]
	v_mfma_f32_16x16x32_bf16 v[90:93], v[224:227], v[220:223], v[90:93]
	v_mfma_f32_16x16x32_bf16 v[86:89], v[228:231], v[220:223], v[86:89]
	v_mfma_f32_16x16x32_bf16 v[82:85], v[232:235], v[220:223], v[82:85]
	s_setprio 0
	s_barrier
	s_setprio 1
	v_mfma_f32_16x16x32_bf16 v[54:57], v[216:219], v[236:239], v[54:57]
	s_add_u32 m0, s17, 0x0
	v_lshl_add_u64 v[204:205], v[188:189], 0, s[4:5]
	global_load_lds_dwordx4 v[204:205], off
	v_mfma_f32_16x16x32_bf16 v[42:45], v[224:227], v[236:239], v[42:45]
	v_mfma_f32_16x16x32_bf16 v[38:41], v[228:231], v[236:239], v[38:41]
	s_add_u32 m0, s17, 0x1000
	v_lshl_add_u64 v[206:207], v[190:191], 0, s[4:5]
	global_load_lds_dwordx4 v[206:207], off
	v_mfma_f32_16x16x32_bf16 v[34:37], v[232:235], v[236:239], v[34:37]
	v_mfma_f32_16x16x32_bf16 v[78:81], v[216:219], v[240:243], v[78:81]
	s_add_u32 m0, s17, 0x2000
	v_lshl_add_u64 v[204:205], v[192:193], 0, s[4:5]
	global_load_lds_dwordx4 v[204:205], off
	v_mfma_f32_16x16x32_bf16 v[74:77], v[224:227], v[240:243], v[74:77]
	v_mfma_f32_16x16x32_bf16 v[70:73], v[228:231], v[240:243], v[70:73]
	s_add_u32 m0, s17, 0x3000
	v_lshl_add_u64 v[206:207], v[194:195], 0, s[4:5]
	global_load_lds_dwordx4 v[206:207], off
	v_mfma_f32_16x16x32_bf16 v[66:69], v[232:235], v[240:243], v[66:69]
	v_mfma_f32_16x16x32_bf16 v[62:65], v[216:219], v[244:247], v[62:65]
	s_add_u32 m0, s17, 0x4000
	v_lshl_add_u64 v[204:205], v[196:197], 0, s[4:5]
	global_load_lds_dwordx4 v[204:205], off
	v_mfma_f32_16x16x32_bf16 v[58:61], v[224:227], v[244:247], v[58:61]
	s_add_u32 m0, s17, 0x5000
	v_lshl_add_u64 v[206:207], v[198:199], 0, s[4:5]
	global_load_lds_dwordx4 v[206:207], off
	v_mfma_f32_16x16x32_bf16 v[50:53], v[228:231], v[244:247], v[50:53]
	s_add_u32 m0, s17, 0x6000
	v_lshl_add_u64 v[204:205], v[200:201], 0, s[4:5]
	global_load_lds_dwordx4 v[204:205], off
	v_mfma_f32_16x16x32_bf16 v[46:49], v[232:235], v[244:247], v[46:49]
	s_add_u32 m0, s17, 0x7000
	v_lshl_add_u64 v[206:207], v[202:203], 0, s[4:5]
	global_load_lds_dwordx4 v[206:207], off
	s_setprio 0
	s_waitcnt vmcnt(8)
	s_barrier
	ds_read_b128 v[152:155], v112 offset:49152
	ds_read_b128 v[156:159], v110 offset:32768
	ds_read_b128 v[160:163], v112 offset:51200
	ds_read_b128 v[164:167], v112 offset:53248
	ds_read_b128 v[168:171], v113 offset:49152
	ds_read_b128 v[172:175], v110 offset:34816
	ds_read_b128 v[208:211], v110 offset:36864
	ds_read_b128 v[212:215], v111 offset:32768
	ds_read_b128 v[216:219], v116 offset:49152
	ds_read_b128 v[220:223], v114 offset:32768
	ds_read_b128 v[224:227], v116 offset:51200
	ds_read_b128 v[228:231], v116 offset:53248
	ds_read_b128 v[232:235], v117 offset:49152
	ds_read_b128 v[236:239], v114 offset:34816
	ds_read_b128 v[240:243], v114 offset:36864
	ds_read_b128 v[244:247], v115 offset:32768
	s_setprio 1
	s_waitcnt lgkmcnt(14)
	v_mfma_f32_16x16x32_bf16 v[94:97], v[152:155], v[156:159], v[94:97]
	s_waitcnt lgkmcnt(13)
	v_mfma_f32_16x16x32_bf16 v[90:93], v[160:163], v[156:159], v[90:93]
	s_waitcnt lgkmcnt(12)
	v_mfma_f32_16x16x32_bf16 v[86:89], v[164:167], v[156:159], v[86:89]
	s_waitcnt lgkmcnt(11)
	v_mfma_f32_16x16x32_bf16 v[82:85], v[168:171], v[156:159], v[82:85]
	s_waitcnt lgkmcnt(10)
	v_mfma_f32_16x16x32_bf16 v[54:57], v[152:155], v[172:175], v[54:57]
	v_mfma_f32_16x16x32_bf16 v[42:45], v[160:163], v[172:175], v[42:45]
	v_mfma_f32_16x16x32_bf16 v[38:41], v[164:167], v[172:175], v[38:41]
	v_mfma_f32_16x16x32_bf16 v[34:37], v[168:171], v[172:175], v[34:37]
	s_waitcnt lgkmcnt(9)
	v_mfma_f32_16x16x32_bf16 v[78:81], v[152:155], v[208:211], v[78:81]
	v_mfma_f32_16x16x32_bf16 v[74:77], v[160:163], v[208:211], v[74:77]
	v_mfma_f32_16x16x32_bf16 v[70:73], v[164:167], v[208:211], v[70:73]
	v_mfma_f32_16x16x32_bf16 v[66:69], v[168:171], v[208:211], v[66:69]
	s_waitcnt lgkmcnt(8)
	v_mfma_f32_16x16x32_bf16 v[62:65], v[152:155], v[212:215], v[62:65]
	v_mfma_f32_16x16x32_bf16 v[58:61], v[160:163], v[212:215], v[58:61]
	v_mfma_f32_16x16x32_bf16 v[50:53], v[164:167], v[212:215], v[50:53]
	v_mfma_f32_16x16x32_bf16 v[46:49], v[168:171], v[212:215], v[46:49]
	s_waitcnt lgkmcnt(0)
	s_add_i32 s4, s16, 0xc0
	s_min_u32 s4, s4, 0x3c0
	s_lshl_b32 s4, s4, 1
	v_mfma_f32_16x16x32_bf16 v[94:97], v[216:219], v[220:223], v[94:97]
	v_mfma_f32_16x16x32_bf16 v[90:93], v[224:227], v[220:223], v[90:93]
	v_mfma_f32_16x16x32_bf16 v[86:89], v[228:231], v[220:223], v[86:89]
	v_mfma_f32_16x16x32_bf16 v[82:85], v[232:235], v[220:223], v[82:85]
	s_setprio 0
	s_barrier
	s_setprio 1
	v_mfma_f32_16x16x32_bf16 v[54:57], v[216:219], v[236:239], v[54:57]
	s_add_u32 m0, s17, 0x8000
	v_lshl_add_u64 v[204:205], v[188:189], 0, s[4:5]
	global_load_lds_dwordx4 v[204:205], off
	v_mfma_f32_16x16x32_bf16 v[42:45], v[224:227], v[236:239], v[42:45]
	v_mfma_f32_16x16x32_bf16 v[38:41], v[228:231], v[236:239], v[38:41]
	s_add_u32 m0, s17, 0x9000
	v_lshl_add_u64 v[206:207], v[190:191], 0, s[4:5]
	global_load_lds_dwordx4 v[206:207], off
	v_mfma_f32_16x16x32_bf16 v[34:37], v[232:235], v[236:239], v[34:37]
	v_mfma_f32_16x16x32_bf16 v[78:81], v[216:219], v[240:243], v[78:81]
	s_add_u32 m0, s17, 0xa000
	v_lshl_add_u64 v[204:205], v[192:193], 0, s[4:5]
	global_load_lds_dwordx4 v[204:205], off
	v_mfma_f32_16x16x32_bf16 v[74:77], v[224:227], v[240:243], v[74:77]
	v_mfma_f32_16x16x32_bf16 v[70:73], v[228:231], v[240:243], v[70:73]
	s_add_u32 m0, s17, 0xb000
	v_lshl_add_u64 v[206:207], v[194:195], 0, s[4:5]
	global_load_lds_dwordx4 v[206:207], off
	v_mfma_f32_16x16x32_bf16 v[66:69], v[232:235], v[240:243], v[66:69]
	v_mfma_f32_16x16x32_bf16 v[62:65], v[216:219], v[244:247], v[62:65]
	s_add_u32 m0, s17, 0xc000
	v_lshl_add_u64 v[204:205], v[196:197], 0, s[4:5]
	global_load_lds_dwordx4 v[204:205], off
	v_mfma_f32_16x16x32_bf16 v[58:61], v[224:227], v[244:247], v[58:61]
	s_add_u32 m0, s17, 0xd000
	v_lshl_add_u64 v[206:207], v[198:199], 0, s[4:5]
	global_load_lds_dwordx4 v[206:207], off
	v_mfma_f32_16x16x32_bf16 v[50:53], v[228:231], v[244:247], v[50:53]
	s_add_u32 m0, s17, 0xe000
	v_lshl_add_u64 v[204:205], v[200:201], 0, s[4:5]
	global_load_lds_dwordx4 v[204:205], off
	v_mfma_f32_16x16x32_bf16 v[46:49], v[232:235], v[244:247], v[46:49]
	s_add_u32 m0, s17, 0xf000
	v_lshl_add_u64 v[206:207], v[202:203], 0, s[4:5]
	global_load_lds_dwordx4 v[206:207], off
	s_setprio 0
	s_waitcnt vmcnt(8)
	s_barrier
	s_add_i32 s16, s16, 0x80
	s_add_i32 s15, s15, 2
	s_cmp_lt_u32 s15, 14
	s_cbranch_scc1 .Lglds2_22142
	s_waitcnt vmcnt(0)
	s_waitcnt vmcnt(7)
	v_or_b32_e32 v2, s14, v119
	s_waitcnt vmcnt(5)
	v_add_u32_e32 v10, s13, v118
	v_mov_b64_e32 v[4:5], s[64:65]
	v_ashrrev_i32_e32 v3, 31, v2
	v_mad_i64_i32 v[6:7], s[14:15], v10, s12, v[4:5]
	v_lshlrev_b64 v[2:3], 1, v[2:3]
	v_lshl_add_u64 v[6:7], v[6:7], 0, v[2:3]
	v_cvt_pk_bf16_f32 v8, v94, v95
	v_cvt_pk_bf16_f32 v9, v96, v97
	global_store_dwordx2 v[6:7], v[8:9], off
	v_cvt_pk_bf16_f32 v8, v90, v91
	v_cvt_pk_bf16_f32 v9, v92, v93
	global_store_dwordx2 v[6:7], v[8:9], off offset:32
	v_cvt_pk_bf16_f32 v8, v86, v87
	v_cvt_pk_bf16_f32 v9, v88, v89
	global_store_dwordx2 v[6:7], v[8:9], off offset:64
	v_cvt_pk_bf16_f32 v8, v82, v83
	v_cvt_pk_bf16_f32 v9, v84, v85
	global_store_dwordx2 v[6:7], v[8:9], off offset:96
	v_or_b32_e32 v6, 16, v10
	v_mad_i64_i32 v[6:7], s[14:15], v6, s12, v[4:5]
	v_lshl_add_u64 v[6:7], v[6:7], 0, v[2:3]
	v_cvt_pk_bf16_f32 v8, v54, v55
	v_cvt_pk_bf16_f32 v9, v56, v57
	global_store_dwordx2 v[6:7], v[8:9], off
	v_cvt_pk_bf16_f32 v8, v42, v43
	v_cvt_pk_bf16_f32 v9, v44, v45
	global_store_dwordx2 v[6:7], v[8:9], off offset:32
	v_cvt_pk_bf16_f32 v8, v38, v39
	v_cvt_pk_bf16_f32 v9, v40, v41
	global_store_dwordx2 v[6:7], v[8:9], off offset:64
	v_cvt_pk_bf16_f32 v8, v34, v35
	v_cvt_pk_bf16_f32 v9, v36, v37
	global_store_dwordx2 v[6:7], v[8:9], off offset:96
	v_or_b32_e32 v6, 32, v10
	v_mad_i64_i32 v[6:7], s[14:15], v6, s12, v[4:5]
	v_lshl_add_u64 v[6:7], v[6:7], 0, v[2:3]
	v_cvt_pk_bf16_f32 v8, v78, v79
	v_cvt_pk_bf16_f32 v9, v80, v81
	global_store_dwordx2 v[6:7], v[8:9], off
	v_cvt_pk_bf16_f32 v8, v74, v75
	v_cvt_pk_bf16_f32 v9, v76, v77
	global_store_dwordx2 v[6:7], v[8:9], off offset:32
	v_cvt_pk_bf16_f32 v8, v70, v71
	v_cvt_pk_bf16_f32 v9, v72, v73
	global_store_dwordx2 v[6:7], v[8:9], off offset:64
	v_cvt_pk_bf16_f32 v8, v66, v67
	v_cvt_pk_bf16_f32 v9, v68, v69
	global_store_dwordx2 v[6:7], v[8:9], off offset:96
	v_or_b32_e32 v6, 48, v10
	v_mad_i64_i32 v[4:5], s[14:15], v6, s12, v[4:5]
	v_lshl_add_u64 v[2:3], v[4:5], 0, v[2:3]
	v_cvt_pk_bf16_f32 v4, v62, v63
	v_cvt_pk_bf16_f32 v5, v64, v65
	global_store_dwordx2 v[2:3], v[4:5], off
	v_cvt_pk_bf16_f32 v4, v58, v59
	v_cvt_pk_bf16_f32 v5, v60, v61
	global_store_dwordx2 v[2:3], v[4:5], off offset:32
	v_cvt_pk_bf16_f32 v4, v50, v51
	v_cvt_pk_bf16_f32 v5, v52, v53
	s_add_i32 s3, s3, s2
	global_store_dwordx2 v[2:3], v[4:5], off offset:64
	v_cvt_pk_bf16_f32 v4, v46, v47
	v_cvt_pk_bf16_f32 v5, v48, v49
	s_cmpk_lt_u32 s3, 0x280
	global_store_dwordx2 v[2:3], v[4:5], off offset:96
	s_cbranch_scc1 .LBB0_664

.Lglds2_26323:
	ds_read_b128 v[152:155], v111 offset:16384
	ds_read_b128 v[156:159], v109
	ds_read_b128 v[160:163], v111 offset:18432
	ds_read_b128 v[164:167], v111 offset:20480
	ds_read_b128 v[168:171], v112 offset:16384
	ds_read_b128 v[172:175], v109 offset:2048
	ds_read_b128 v[208:211], v109 offset:4096
	ds_read_b128 v[212:215], v110
	ds_read_b128 v[216:219], v115 offset:16384
	ds_read_b128 v[220:223], v113
	ds_read_b128 v[224:227], v115 offset:18432
	ds_read_b128 v[228:231], v115 offset:20480
	ds_read_b128 v[232:235], v116 offset:16384
	ds_read_b128 v[236:239], v113 offset:2048
	ds_read_b128 v[240:243], v113 offset:4096
	ds_read_b128 v[244:247], v114
	s_setprio 1
	s_waitcnt lgkmcnt(14)
	v_mfma_f32_16x16x32_bf16 v[92:95], v[152:155], v[156:159], v[92:95]
	s_waitcnt lgkmcnt(13)
	v_mfma_f32_16x16x32_bf16 v[88:91], v[160:163], v[156:159], v[88:91]
	s_waitcnt lgkmcnt(12)
	v_mfma_f32_16x16x32_bf16 v[84:87], v[164:167], v[156:159], v[84:87]
	s_waitcnt lgkmcnt(11)
	v_mfma_f32_16x16x32_bf16 v[80:83], v[168:171], v[156:159], v[80:83]
	s_waitcnt lgkmcnt(10)
	v_mfma_f32_16x16x32_bf16 v[76:79], v[152:155], v[172:175], v[76:79]
	v_mfma_f32_16x16x32_bf16 v[72:75], v[160:163], v[172:175], v[72:75]
	v_mfma_f32_16x16x32_bf16 v[60:63], v[164:167], v[172:175], v[60:63]
	v_mfma_f32_16x16x32_bf16 v[28:31], v[168:171], v[172:175], v[28:31]
	s_waitcnt lgkmcnt(9)
	v_mfma_f32_16x16x32_bf16 v[64:67], v[152:155], v[208:211], v[64:67]
	v_mfma_f32_16x16x32_bf16 v[36:39], v[160:163], v[208:211], v[36:39]
	v_mfma_f32_16x16x32_bf16 v[32:35], v[164:167], v[208:211], v[32:35]
	v_mfma_f32_16x16x32_bf16 v[16:19], v[168:171], v[208:211], v[16:19]
	s_waitcnt lgkmcnt(8)
	v_mfma_f32_16x16x32_bf16 v[12:15], v[152:155], v[212:215], v[12:15]
	v_mfma_f32_16x16x32_bf16 v[8:11], v[160:163], v[212:215], v[8:11]
	v_mfma_f32_16x16x32_bf16 v[4:7], v[164:167], v[212:215], v[4:7]
	v_mfma_f32_16x16x32_bf16 v[0:3], v[168:171], v[212:215], v[0:3]
	s_waitcnt lgkmcnt(0)
	s_add_i32 s4, s14, 0x80
	s_min_u32 s4, s4, 0x3c0
	s_lshl_b32 s4, s4, 1
	v_mfma_f32_16x16x32_bf16 v[92:95], v[216:219], v[220:223], v[92:95]
	v_mfma_f32_16x16x32_bf16 v[88:91], v[224:227], v[220:223], v[88:91]
	v_mfma_f32_16x16x32_bf16 v[84:87], v[228:231], v[220:223], v[84:87]
	v_mfma_f32_16x16x32_bf16 v[80:83], v[232:235], v[220:223], v[80:83]
	s_setprio 0
	s_barrier
	s_setprio 1
	v_mfma_f32_16x16x32_bf16 v[76:79], v[216:219], v[236:239], v[76:79]
	s_add_u32 m0, s15, 0x0
	v_lshl_add_u64 v[204:205], v[188:189], 0, s[4:5]
	global_load_lds_dwordx4 v[204:205], off
	v_mfma_f32_16x16x32_bf16 v[72:75], v[224:227], v[236:239], v[72:75]
	v_mfma_f32_16x16x32_bf16 v[60:63], v[228:231], v[236:239], v[60:63]
	s_add_u32 m0, s15, 0x1000
	v_lshl_add_u64 v[206:207], v[190:191], 0, s[4:5]
	global_load_lds_dwordx4 v[206:207], off
	v_mfma_f32_16x16x32_bf16 v[28:31], v[232:235], v[236:239], v[28:31]
	v_mfma_f32_16x16x32_bf16 v[64:67], v[216:219], v[240:243], v[64:67]
	s_add_u32 m0, s15, 0x2000
	v_lshl_add_u64 v[204:205], v[192:193], 0, s[4:5]
	global_load_lds_dwordx4 v[204:205], off
	v_mfma_f32_16x16x32_bf16 v[36:39], v[224:227], v[240:243], v[36:39]
	v_mfma_f32_16x16x32_bf16 v[32:35], v[228:231], v[240:243], v[32:35]
	s_add_u32 m0, s15, 0x3000
	v_lshl_add_u64 v[206:207], v[194:195], 0, s[4:5]
	global_load_lds_dwordx4 v[206:207], off
	v_mfma_f32_16x16x32_bf16 v[16:19], v[232:235], v[240:243], v[16:19]
	v_mfma_f32_16x16x32_bf16 v[12:15], v[216:219], v[244:247], v[12:15]
	s_add_u32 m0, s15, 0x4000
	v_lshl_add_u64 v[204:205], v[196:197], 0, s[4:5]
	global_load_lds_dwordx4 v[204:205], off
	v_mfma_f32_16x16x32_bf16 v[8:11], v[224:227], v[244:247], v[8:11]
	s_add_u32 m0, s15, 0x5000
	v_lshl_add_u64 v[206:207], v[198:199], 0, s[4:5]
	global_load_lds_dwordx4 v[206:207], off
	v_mfma_f32_16x16x32_bf16 v[4:7], v[228:231], v[244:247], v[4:7]
	s_add_u32 m0, s15, 0x6000
	v_lshl_add_u64 v[204:205], v[200:201], 0, s[4:5]
	global_load_lds_dwordx4 v[204:205], off
	v_mfma_f32_16x16x32_bf16 v[0:3], v[232:235], v[244:247], v[0:3]
	s_add_u32 m0, s15, 0x7000
	v_lshl_add_u64 v[206:207], v[202:203], 0, s[4:5]
	global_load_lds_dwordx4 v[206:207], off
	s_setprio 0
	s_waitcnt vmcnt(8)
	s_barrier
	ds_read_b128 v[152:155], v111 offset:49152
	ds_read_b128 v[156:159], v109 offset:32768
	ds_read_b128 v[160:163], v111 offset:51200
	ds_read_b128 v[164:167], v111 offset:53248
	ds_read_b128 v[168:171], v112 offset:49152
	ds_read_b128 v[172:175], v109 offset:34816
	ds_read_b128 v[208:211], v109 offset:36864
	ds_read_b128 v[212:215], v110 offset:32768
	ds_read_b128 v[216:219], v115 offset:49152
	ds_read_b128 v[220:223], v113 offset:32768
	ds_read_b128 v[224:227], v115 offset:51200
	ds_read_b128 v[228:231], v115 offset:53248
	ds_read_b128 v[232:235], v116 offset:49152
	ds_read_b128 v[236:239], v113 offset:34816
	ds_read_b128 v[240:243], v113 offset:36864
	ds_read_b128 v[244:247], v114 offset:32768
	s_setprio 1
	s_waitcnt lgkmcnt(14)
	v_mfma_f32_16x16x32_bf16 v[92:95], v[152:155], v[156:159], v[92:95]
	s_waitcnt lgkmcnt(13)
	v_mfma_f32_16x16x32_bf16 v[88:91], v[160:163], v[156:159], v[88:91]
	s_waitcnt lgkmcnt(12)
	v_mfma_f32_16x16x32_bf16 v[84:87], v[164:167], v[156:159], v[84:87]
	s_waitcnt lgkmcnt(11)
	v_mfma_f32_16x16x32_bf16 v[80:83], v[168:171], v[156:159], v[80:83]
	s_waitcnt lgkmcnt(10)
	v_mfma_f32_16x16x32_bf16 v[76:79], v[152:155], v[172:175], v[76:79]
	v_mfma_f32_16x16x32_bf16 v[72:75], v[160:163], v[172:175], v[72:75]
	v_mfma_f32_16x16x32_bf16 v[60:63], v[164:167], v[172:175], v[60:63]
	v_mfma_f32_16x16x32_bf16 v[28:31], v[168:171], v[172:175], v[28:31]
	s_waitcnt lgkmcnt(9)
	v_mfma_f32_16x16x32_bf16 v[64:67], v[152:155], v[208:211], v[64:67]
	v_mfma_f32_16x16x32_bf16 v[36:39], v[160:163], v[208:211], v[36:39]
	v_mfma_f32_16x16x32_bf16 v[32:35], v[164:167], v[208:211], v[32:35]
	v_mfma_f32_16x16x32_bf16 v[16:19], v[168:171], v[208:211], v[16:19]
	s_waitcnt lgkmcnt(8)
	v_mfma_f32_16x16x32_bf16 v[12:15], v[152:155], v[212:215], v[12:15]
	v_mfma_f32_16x16x32_bf16 v[8:11], v[160:163], v[212:215], v[8:11]
	v_mfma_f32_16x16x32_bf16 v[4:7], v[164:167], v[212:215], v[4:7]
	v_mfma_f32_16x16x32_bf16 v[0:3], v[168:171], v[212:215], v[0:3]
	s_waitcnt lgkmcnt(0)
	s_add_i32 s4, s14, 0xc0
	s_min_u32 s4, s4, 0x3c0
	s_lshl_b32 s4, s4, 1
	v_mfma_f32_16x16x32_bf16 v[92:95], v[216:219], v[220:223], v[92:95]
	v_mfma_f32_16x16x32_bf16 v[88:91], v[224:227], v[220:223], v[88:91]
	v_mfma_f32_16x16x32_bf16 v[84:87], v[228:231], v[220:223], v[84:87]
	v_mfma_f32_16x16x32_bf16 v[80:83], v[232:235], v[220:223], v[80:83]
	s_setprio 0
	s_barrier
	s_setprio 1
	v_mfma_f32_16x16x32_bf16 v[76:79], v[216:219], v[236:239], v[76:79]
	s_add_u32 m0, s15, 0x8000
	v_lshl_add_u64 v[204:205], v[188:189], 0, s[4:5]
	global_load_lds_dwordx4 v[204:205], off
	v_mfma_f32_16x16x32_bf16 v[72:75], v[224:227], v[236:239], v[72:75]
	v_mfma_f32_16x16x32_bf16 v[60:63], v[228:231], v[236:239], v[60:63]
	s_add_u32 m0, s15, 0x9000
	v_lshl_add_u64 v[206:207], v[190:191], 0, s[4:5]
	global_load_lds_dwordx4 v[206:207], off
	v_mfma_f32_16x16x32_bf16 v[28:31], v[232:235], v[236:239], v[28:31]
	v_mfma_f32_16x16x32_bf16 v[64:67], v[216:219], v[240:243], v[64:67]
	s_add_u32 m0, s15, 0xa000
	v_lshl_add_u64 v[204:205], v[192:193], 0, s[4:5]
	global_load_lds_dwordx4 v[204:205], off
	v_mfma_f32_16x16x32_bf16 v[36:39], v[224:227], v[240:243], v[36:39]
	v_mfma_f32_16x16x32_bf16 v[32:35], v[228:231], v[240:243], v[32:35]
	s_add_u32 m0, s15, 0xb000
	v_lshl_add_u64 v[206:207], v[194:195], 0, s[4:5]
	global_load_lds_dwordx4 v[206:207], off
	v_mfma_f32_16x16x32_bf16 v[16:19], v[232:235], v[240:243], v[16:19]
	v_mfma_f32_16x16x32_bf16 v[12:15], v[216:219], v[244:247], v[12:15]
	s_add_u32 m0, s15, 0xc000
	v_lshl_add_u64 v[204:205], v[196:197], 0, s[4:5]
	global_load_lds_dwordx4 v[204:205], off
	v_mfma_f32_16x16x32_bf16 v[8:11], v[224:227], v[244:247], v[8:11]
	s_add_u32 m0, s15, 0xd000
	v_lshl_add_u64 v[206:207], v[198:199], 0, s[4:5]
	global_load_lds_dwordx4 v[206:207], off
	v_mfma_f32_16x16x32_bf16 v[4:7], v[228:231], v[244:247], v[4:7]
	s_add_u32 m0, s15, 0xe000
	v_lshl_add_u64 v[204:205], v[200:201], 0, s[4:5]
	global_load_lds_dwordx4 v[204:205], off
	v_mfma_f32_16x16x32_bf16 v[0:3], v[232:235], v[244:247], v[0:3]
	s_add_u32 m0, s15, 0xf000
	v_lshl_add_u64 v[206:207], v[202:203], 0, s[4:5]
	global_load_lds_dwordx4 v[206:207], off
	s_setprio 0
	s_waitcnt vmcnt(8)
	s_barrier
	s_add_i32 s14, s14, 0x80
	s_add_i32 s13, s13, 2
	s_cmp_lt_u32 s13, 14
	s_cbranch_scc1 .Lglds2_26323
	s_waitcnt vmcnt(0)
	s_waitcnt vmcnt(0)
	v_or_b32_e32 v170, s12, v118
	v_add_lshl_u32 v96, v117, s11, 10
	v_readlane_b32 s12, v254, 24
	v_readlane_b32 s16, v254, 28
	v_readlane_b32 s17, v254, 29
	v_readlane_b32 s13, v254, 25
	v_readlane_b32 s14, v254, 26
	v_readlane_b32 s15, v254, 27
	v_readlane_b32 s18, v254, 30
	v_readlane_b32 s19, v254, 31
	v_readlane_b32 s20, v254, 32
	v_readlane_b32 s21, v254, 33
	v_readlane_b32 s22, v254, 34
	v_readlane_b32 s23, v254, 35
	v_readlane_b32 s24, v254, 36
	v_readlane_b32 s25, v254, 37
	v_readlane_b32 s26, v254, 38
	v_readlane_b32 s27, v254, 39
	v_lshlrev_b32_e32 v168, 2, v170
	v_mov_b32_e32 v169, v97
	v_lshlrev_b64 v[174:175], 2, v[96:97]
	v_lshl_add_u64 v[152:153], s[16:17], 0, v[174:175]
	v_lshl_add_u64 v[160:161], s[82:83], 0, v[174:175]
	v_lshl_add_u64 v[152:153], v[152:153], 0, v[168:169]
	v_lshl_add_u64 v[160:161], v[160:161], 0, v[168:169]
	global_load_dwordx4 v[120:123], v[152:153], off
	global_load_dwordx4 v[124:127], v[152:153], off offset:64
	global_load_dwordx4 v[128:131], v[152:153], off offset:128
	global_load_dwordx4 v[132:135], v[152:153], off offset:192
	v_or_b32_e32 v172, 0x4000, v96
	v_mov_b32_e32 v173, v97
	v_lshlrev_b64 v[174:175], 2, v[172:173]
	v_lshl_add_u64 v[154:155], s[16:17], 0, v[174:175]
	v_lshl_add_u64 v[162:163], s[82:83], 0, v[174:175]
	v_lshl_add_u64 v[154:155], v[154:155], 0, v[168:169]
	v_lshl_add_u64 v[162:163], v[162:163], 0, v[168:169]
	global_load_dwordx4 v[136:139], v[154:155], off
	global_load_dwordx4 v[140:143], v[154:155], off offset:64
	global_load_dwordx4 v[144:147], v[154:155], off offset:128
	global_load_dwordx4 v[148:151], v[154:155], off offset:192
	v_or_b32_e32 v172, 0x8000, v96
	v_mov_b32_e32 v173, v97
	v_lshlrev_b64 v[174:175], 2, v[172:173]
	v_lshl_add_u64 v[156:157], s[16:17], 0, v[174:175]
	v_lshl_add_u64 v[164:165], s[82:83], 0, v[174:175]
	v_lshl_add_u64 v[156:157], v[156:157], 0, v[168:169]
	v_lshl_add_u64 v[164:165], v[164:165], 0, v[168:169]
	global_load_dwordx4 v[20:23], v[156:157], off
	global_load_dwordx4 v[24:27], v[156:157], off offset:64
	global_load_dwordx4 v[40:43], v[156:157], off offset:128
	global_load_dwordx4 v[44:47], v[156:157], off offset:192
	v_or_b32_e32 v172, 0xc000, v96
	v_mov_b32_e32 v173, v97
	v_lshlrev_b64 v[174:175], 2, v[172:173]
	v_lshl_add_u64 v[158:159], s[16:17], 0, v[174:175]
	v_lshl_add_u64 v[166:167], s[82:83], 0, v[174:175]
	v_lshl_add_u64 v[158:159], v[158:159], 0, v[168:169]
	v_lshl_add_u64 v[166:167], v[166:167], 0, v[168:169]
	global_load_dwordx4 v[48:51], v[158:159], off
	global_load_dwordx4 v[52:55], v[158:159], off offset:64
	global_load_dwordx4 v[56:59], v[158:159], off offset:128
	global_load_dwordx4 v[68:71], v[158:159], off offset:192
	s_waitcnt vmcnt(15)
	v_pk_fma_f32 v[120:121], v[120:121], s[6:7], v[92:93] op_sel_hi:[1,0,1]
	v_pk_fma_f32 v[122:123], v[122:123], s[6:7], v[94:95] op_sel_hi:[1,0,1]
	s_waitcnt vmcnt(14)
	v_pk_fma_f32 v[124:125], v[124:125], s[6:7], v[88:89] op_sel_hi:[1,0,1]
	v_pk_fma_f32 v[126:127], v[126:127], s[6:7], v[90:91] op_sel_hi:[1,0,1]
	s_waitcnt vmcnt(13)
	v_pk_fma_f32 v[128:129], v[128:129], s[6:7], v[84:85] op_sel_hi:[1,0,1]
	v_pk_fma_f32 v[130:131], v[130:131], s[6:7], v[86:87] op_sel_hi:[1,0,1]
	s_waitcnt vmcnt(12)
	v_pk_fma_f32 v[132:133], v[132:133], s[6:7], v[80:81] op_sel_hi:[1,0,1]
	v_pk_fma_f32 v[134:135], v[134:135], s[6:7], v[82:83] op_sel_hi:[1,0,1]
	s_waitcnt vmcnt(11)
	v_pk_fma_f32 v[136:137], v[136:137], s[6:7], v[76:77] op_sel_hi:[1,0,1]
	v_pk_fma_f32 v[138:139], v[138:139], s[6:7], v[78:79] op_sel_hi:[1,0,1]
	s_waitcnt vmcnt(10)
	v_pk_fma_f32 v[140:141], v[140:141], s[6:7], v[72:73] op_sel_hi:[1,0,1]
	v_pk_fma_f32 v[142:143], v[142:143], s[6:7], v[74:75] op_sel_hi:[1,0,1]
	s_waitcnt vmcnt(9)
	v_pk_fma_f32 v[144:145], v[144:145], s[6:7], v[60:61] op_sel_hi:[1,0,1]
	v_pk_fma_f32 v[146:147], v[146:147], s[6:7], v[62:63] op_sel_hi:[1,0,1]
	s_waitcnt vmcnt(8)
	v_pk_fma_f32 v[148:149], v[148:149], s[6:7], v[28:29] op_sel_hi:[1,0,1]
	v_pk_fma_f32 v[150:151], v[150:151], s[6:7], v[30:31] op_sel_hi:[1,0,1]
	s_waitcnt vmcnt(7)
	v_pk_fma_f32 v[20:21], v[20:21], s[6:7], v[64:65] op_sel_hi:[1,0,1]
	v_pk_fma_f32 v[22:23], v[22:23], s[6:7], v[66:67] op_sel_hi:[1,0,1]
	s_waitcnt vmcnt(6)
	v_pk_fma_f32 v[24:25], v[24:25], s[6:7], v[36:37] op_sel_hi:[1,0,1]
	v_pk_fma_f32 v[26:27], v[26:27], s[6:7], v[38:39] op_sel_hi:[1,0,1]
	s_waitcnt vmcnt(5)
	v_pk_fma_f32 v[40:41], v[40:41], s[6:7], v[32:33] op_sel_hi:[1,0,1]
	v_pk_fma_f32 v[42:43], v[42:43], s[6:7], v[34:35] op_sel_hi:[1,0,1]
	s_waitcnt vmcnt(4)
	v_pk_fma_f32 v[44:45], v[44:45], s[6:7], v[16:17] op_sel_hi:[1,0,1]
	v_pk_fma_f32 v[46:47], v[46:47], s[6:7], v[18:19] op_sel_hi:[1,0,1]
	s_waitcnt vmcnt(3)
	v_pk_fma_f32 v[48:49], v[48:49], s[6:7], v[12:13] op_sel_hi:[1,0,1]
	v_pk_fma_f32 v[50:51], v[50:51], s[6:7], v[14:15] op_sel_hi:[1,0,1]
	s_waitcnt vmcnt(2)
	v_pk_fma_f32 v[52:53], v[52:53], s[6:7], v[8:9] op_sel_hi:[1,0,1]
	v_pk_fma_f32 v[54:55], v[54:55], s[6:7], v[10:11] op_sel_hi:[1,0,1]
	s_waitcnt vmcnt(1)
	v_pk_fma_f32 v[56:57], v[56:57], s[6:7], v[4:5] op_sel_hi:[1,0,1]
	v_pk_fma_f32 v[58:59], v[58:59], s[6:7], v[6:7] op_sel_hi:[1,0,1]
	s_waitcnt vmcnt(0)
	v_pk_fma_f32 v[68:69], v[68:69], s[6:7], v[0:1] op_sel_hi:[1,0,1]
	v_pk_fma_f32 v[70:71], v[70:71], s[6:7], v[2:3] op_sel_hi:[1,0,1]
	global_store_dwordx4 v[160:161], v[120:123], off
	global_store_dwordx4 v[160:161], v[124:127], off offset:64
	global_store_dwordx4 v[160:161], v[128:131], off offset:128
	global_store_dwordx4 v[160:161], v[132:135], off offset:192
	global_store_dwordx4 v[162:163], v[136:139], off
	global_store_dwordx4 v[162:163], v[140:143], off offset:64
	global_store_dwordx4 v[162:163], v[144:147], off offset:128
	global_store_dwordx4 v[162:163], v[148:151], off offset:192
	global_store_dwordx4 v[164:165], v[20:23], off
	global_store_dwordx4 v[164:165], v[24:27], off offset:64
	global_store_dwordx4 v[164:165], v[40:43], off offset:128
	global_store_dwordx4 v[164:165], v[44:47], off offset:192
	global_store_dwordx4 v[166:167], v[48:51], off
	global_store_dwordx4 v[166:167], v[52:55], off offset:64
	global_store_dwordx4 v[166:167], v[56:59], off offset:128
	global_store_dwordx4 v[166:167], v[68:71], off offset:192
	s_add_i32 s7, s7, s3
	s_cmpk_lt_u32 s7, 0x100
	s_cbranch_scc1 .LBB0_798

.Lglds2_28042:
	ds_read_b128 v[152:155], v111 offset:16384
	ds_read_b128 v[156:159], v109
	ds_read_b128 v[160:163], v111 offset:18432
	ds_read_b128 v[164:167], v111 offset:20480
	ds_read_b128 v[168:171], v112 offset:16384
	ds_read_b128 v[172:175], v109 offset:2048
	ds_read_b128 v[208:211], v109 offset:4096
	ds_read_b128 v[212:215], v110
	ds_read_b128 v[216:219], v115 offset:16384
	ds_read_b128 v[220:223], v113
	ds_read_b128 v[224:227], v115 offset:18432
	ds_read_b128 v[228:231], v115 offset:20480
	ds_read_b128 v[232:235], v116 offset:16384
	ds_read_b128 v[236:239], v113 offset:2048
	ds_read_b128 v[240:243], v113 offset:4096
	ds_read_b128 v[244:247], v114
	s_setprio 1
	s_waitcnt lgkmcnt(14)
	v_mfma_i32_16x16x64_i8 v[92:95], v[152:155], v[156:159], v[92:95]
	s_waitcnt lgkmcnt(13)
	v_mfma_i32_16x16x64_i8 v[88:91], v[160:163], v[156:159], v[88:91]
	s_waitcnt lgkmcnt(12)
	v_mfma_i32_16x16x64_i8 v[84:87], v[164:167], v[156:159], v[84:87]
	s_waitcnt lgkmcnt(11)
	v_mfma_i32_16x16x64_i8 v[80:83], v[168:171], v[156:159], v[80:83]
	s_waitcnt lgkmcnt(10)
	v_mfma_i32_16x16x64_i8 v[60:63], v[152:155], v[172:175], v[60:63]
	v_mfma_i32_16x16x64_i8 v[40:43], v[160:163], v[172:175], v[40:43]
	v_mfma_i32_16x16x64_i8 v[36:39], v[164:167], v[172:175], v[36:39]
	v_mfma_i32_16x16x64_i8 v[28:31], v[168:171], v[172:175], v[28:31]
	s_waitcnt lgkmcnt(9)
	v_mfma_i32_16x16x64_i8 v[32:35], v[152:155], v[208:211], v[32:35]
	v_mfma_i32_16x16x64_i8 v[24:27], v[160:163], v[208:211], v[24:27]
	v_mfma_i32_16x16x64_i8 v[20:23], v[164:167], v[208:211], v[20:23]
	v_mfma_i32_16x16x64_i8 v[16:19], v[168:171], v[208:211], v[16:19]
	s_waitcnt lgkmcnt(8)
	v_mfma_i32_16x16x64_i8 v[12:15], v[152:155], v[212:215], v[12:15]
	v_mfma_i32_16x16x64_i8 v[8:11], v[160:163], v[212:215], v[8:11]
	v_mfma_i32_16x16x64_i8 v[4:7], v[164:167], v[212:215], v[4:7]
	v_mfma_i32_16x16x64_i8 v[0:3], v[168:171], v[212:215], v[0:3]
	s_waitcnt lgkmcnt(0)
	s_add_i32 s6, s15, 0x80
	s_min_u32 s6, s6, 0x1c0
	s_lshl_b32 s6, s6, 1
	v_mfma_i32_16x16x64_i8 v[92:95], v[216:219], v[220:223], v[92:95]
	v_mfma_i32_16x16x64_i8 v[88:91], v[224:227], v[220:223], v[88:91]
	v_mfma_i32_16x16x64_i8 v[84:87], v[228:231], v[220:223], v[84:87]
	v_mfma_i32_16x16x64_i8 v[80:83], v[232:235], v[220:223], v[80:83]
	s_setprio 0
	s_barrier
	s_setprio 1
	v_mfma_i32_16x16x64_i8 v[60:63], v[216:219], v[236:239], v[60:63]
	s_add_u32 m0, s16, 0x0
	v_lshl_add_u64 v[204:205], v[188:189], 0, s[6:7]
	global_load_lds_dwordx4 v[204:205], off
	v_mfma_i32_16x16x64_i8 v[40:43], v[224:227], v[236:239], v[40:43]
	v_mfma_i32_16x16x64_i8 v[36:39], v[228:231], v[236:239], v[36:39]
	s_add_u32 m0, s16, 0x1000
	v_lshl_add_u64 v[206:207], v[190:191], 0, s[6:7]
	global_load_lds_dwordx4 v[206:207], off
	v_mfma_i32_16x16x64_i8 v[28:31], v[232:235], v[236:239], v[28:31]
	v_mfma_i32_16x16x64_i8 v[32:35], v[216:219], v[240:243], v[32:35]
	s_add_u32 m0, s16, 0x2000
	v_lshl_add_u64 v[204:205], v[192:193], 0, s[6:7]
	global_load_lds_dwordx4 v[204:205], off
	v_mfma_i32_16x16x64_i8 v[24:27], v[224:227], v[240:243], v[24:27]
	v_mfma_i32_16x16x64_i8 v[20:23], v[228:231], v[240:243], v[20:23]
	s_add_u32 m0, s16, 0x3000
	v_lshl_add_u64 v[206:207], v[194:195], 0, s[6:7]
	global_load_lds_dwordx4 v[206:207], off
	v_mfma_i32_16x16x64_i8 v[16:19], v[232:235], v[240:243], v[16:19]
	v_mfma_i32_16x16x64_i8 v[12:15], v[216:219], v[244:247], v[12:15]
	s_add_u32 m0, s16, 0x4000
	v_lshl_add_u64 v[204:205], v[196:197], 0, s[6:7]
	global_load_lds_dwordx4 v[204:205], off
	v_mfma_i32_16x16x64_i8 v[8:11], v[224:227], v[244:247], v[8:11]
	s_add_u32 m0, s16, 0x5000
	v_lshl_add_u64 v[206:207], v[198:199], 0, s[6:7]
	global_load_lds_dwordx4 v[206:207], off
	v_mfma_i32_16x16x64_i8 v[4:7], v[228:231], v[244:247], v[4:7]
	s_add_u32 m0, s16, 0x6000
	v_lshl_add_u64 v[204:205], v[200:201], 0, s[6:7]
	global_load_lds_dwordx4 v[204:205], off
	v_mfma_i32_16x16x64_i8 v[0:3], v[232:235], v[244:247], v[0:3]
	s_add_u32 m0, s16, 0x7000
	v_lshl_add_u64 v[206:207], v[202:203], 0, s[6:7]
	global_load_lds_dwordx4 v[206:207], off
	s_setprio 0
	s_waitcnt vmcnt(8)
	s_barrier
	ds_read_b128 v[152:155], v111 offset:49152
	ds_read_b128 v[156:159], v109 offset:32768
	ds_read_b128 v[160:163], v111 offset:51200
	ds_read_b128 v[164:167], v111 offset:53248
	ds_read_b128 v[168:171], v112 offset:49152
	ds_read_b128 v[172:175], v109 offset:34816
	ds_read_b128 v[208:211], v109 offset:36864
	ds_read_b128 v[212:215], v110 offset:32768
	ds_read_b128 v[216:219], v115 offset:49152
	ds_read_b128 v[220:223], v113 offset:32768
	ds_read_b128 v[224:227], v115 offset:51200
	ds_read_b128 v[228:231], v115 offset:53248
	ds_read_b128 v[232:235], v116 offset:49152
	ds_read_b128 v[236:239], v113 offset:34816
	ds_read_b128 v[240:243], v113 offset:36864
	ds_read_b128 v[244:247], v114 offset:32768
	s_setprio 1
	s_waitcnt lgkmcnt(14)
	v_mfma_i32_16x16x64_i8 v[92:95], v[152:155], v[156:159], v[92:95]
	s_waitcnt lgkmcnt(13)
	v_mfma_i32_16x16x64_i8 v[88:91], v[160:163], v[156:159], v[88:91]
	s_waitcnt lgkmcnt(12)
	v_mfma_i32_16x16x64_i8 v[84:87], v[164:167], v[156:159], v[84:87]
	s_waitcnt lgkmcnt(11)
	v_mfma_i32_16x16x64_i8 v[80:83], v[168:171], v[156:159], v[80:83]
	s_waitcnt lgkmcnt(10)
	v_mfma_i32_16x16x64_i8 v[60:63], v[152:155], v[172:175], v[60:63]
	v_mfma_i32_16x16x64_i8 v[40:43], v[160:163], v[172:175], v[40:43]
	v_mfma_i32_16x16x64_i8 v[36:39], v[164:167], v[172:175], v[36:39]
	v_mfma_i32_16x16x64_i8 v[28:31], v[168:171], v[172:175], v[28:31]
	s_waitcnt lgkmcnt(9)
	v_mfma_i32_16x16x64_i8 v[32:35], v[152:155], v[208:211], v[32:35]
	v_mfma_i32_16x16x64_i8 v[24:27], v[160:163], v[208:211], v[24:27]
	v_mfma_i32_16x16x64_i8 v[20:23], v[164:167], v[208:211], v[20:23]
	v_mfma_i32_16x16x64_i8 v[16:19], v[168:171], v[208:211], v[16:19]
	s_waitcnt lgkmcnt(8)
	v_mfma_i32_16x16x64_i8 v[12:15], v[152:155], v[212:215], v[12:15]
	v_mfma_i32_16x16x64_i8 v[8:11], v[160:163], v[212:215], v[8:11]
	v_mfma_i32_16x16x64_i8 v[4:7], v[164:167], v[212:215], v[4:7]
	v_mfma_i32_16x16x64_i8 v[0:3], v[168:171], v[212:215], v[0:3]
	s_waitcnt lgkmcnt(0)
	s_add_i32 s6, s15, 0xc0
	s_min_u32 s6, s6, 0x1c0
	s_lshl_b32 s6, s6, 1
	v_mfma_i32_16x16x64_i8 v[92:95], v[216:219], v[220:223], v[92:95]
	v_mfma_i32_16x16x64_i8 v[88:91], v[224:227], v[220:223], v[88:91]
	v_mfma_i32_16x16x64_i8 v[84:87], v[228:231], v[220:223], v[84:87]
	v_mfma_i32_16x16x64_i8 v[80:83], v[232:235], v[220:223], v[80:83]
	s_setprio 0
	s_barrier
	s_setprio 1
	v_mfma_i32_16x16x64_i8 v[60:63], v[216:219], v[236:239], v[60:63]
	s_add_u32 m0, s16, 0x8000
	v_lshl_add_u64 v[204:205], v[188:189], 0, s[6:7]
	global_load_lds_dwordx4 v[204:205], off
	v_mfma_i32_16x16x64_i8 v[40:43], v[224:227], v[236:239], v[40:43]
	v_mfma_i32_16x16x64_i8 v[36:39], v[228:231], v[236:239], v[36:39]
	s_add_u32 m0, s16, 0x9000
	v_lshl_add_u64 v[206:207], v[190:191], 0, s[6:7]
	global_load_lds_dwordx4 v[206:207], off
	v_mfma_i32_16x16x64_i8 v[28:31], v[232:235], v[236:239], v[28:31]
	v_mfma_i32_16x16x64_i8 v[32:35], v[216:219], v[240:243], v[32:35]
	s_add_u32 m0, s16, 0xa000
	v_lshl_add_u64 v[204:205], v[192:193], 0, s[6:7]
	global_load_lds_dwordx4 v[204:205], off
	v_mfma_i32_16x16x64_i8 v[24:27], v[224:227], v[240:243], v[24:27]
	v_mfma_i32_16x16x64_i8 v[20:23], v[228:231], v[240:243], v[20:23]
	s_add_u32 m0, s16, 0xb000
	v_lshl_add_u64 v[206:207], v[194:195], 0, s[6:7]
	global_load_lds_dwordx4 v[206:207], off
	v_mfma_i32_16x16x64_i8 v[16:19], v[232:235], v[240:243], v[16:19]
	v_mfma_i32_16x16x64_i8 v[12:15], v[216:219], v[244:247], v[12:15]
	s_add_u32 m0, s16, 0xc000
	v_lshl_add_u64 v[204:205], v[196:197], 0, s[6:7]
	global_load_lds_dwordx4 v[204:205], off
	v_mfma_i32_16x16x64_i8 v[8:11], v[224:227], v[244:247], v[8:11]
	s_add_u32 m0, s16, 0xd000
	v_lshl_add_u64 v[206:207], v[198:199], 0, s[6:7]
	global_load_lds_dwordx4 v[206:207], off
	v_mfma_i32_16x16x64_i8 v[4:7], v[228:231], v[244:247], v[4:7]
	s_add_u32 m0, s16, 0xe000
	v_lshl_add_u64 v[204:205], v[200:201], 0, s[6:7]
	global_load_lds_dwordx4 v[204:205], off
	v_mfma_i32_16x16x64_i8 v[0:3], v[232:235], v[244:247], v[0:3]
	s_add_u32 m0, s16, 0xf000
	v_lshl_add_u64 v[206:207], v[202:203], 0, s[6:7]
	global_load_lds_dwordx4 v[206:207], off
	s_setprio 0
	s_waitcnt vmcnt(8)
	s_barrier
	s_add_i32 s15, s15, 0x80
	s_add_i32 s14, s14, 2
	s_cmp_lt_u32 s14, 6
	s_cbranch_scc1 .Lglds2_28042
	s_waitcnt vmcnt(0)
	v_cvt_f32_i32_e32 v92, v92
	v_cvt_f32_i32_e32 v93, v93
	v_cvt_f32_i32_e32 v94, v94
	v_cvt_f32_i32_e32 v95, v95
	v_cvt_f32_i32_e32 v88, v88
	v_cvt_f32_i32_e32 v89, v89
	v_cvt_f32_i32_e32 v90, v90
	v_cvt_f32_i32_e32 v91, v91
	v_cvt_f32_i32_e32 v84, v84
	v_cvt_f32_i32_e32 v85, v85
	v_cvt_f32_i32_e32 v86, v86
	v_cvt_f32_i32_e32 v87, v87
	v_cvt_f32_i32_e32 v80, v80
	v_cvt_f32_i32_e32 v81, v81
	v_cvt_f32_i32_e32 v82, v82
	v_cvt_f32_i32_e32 v83, v83
	v_cvt_f32_i32_e32 v60, v60
	v_cvt_f32_i32_e32 v61, v61
	v_cvt_f32_i32_e32 v62, v62
	v_cvt_f32_i32_e32 v63, v63
	v_cvt_f32_i32_e32 v40, v40
	v_cvt_f32_i32_e32 v41, v41
	v_cvt_f32_i32_e32 v42, v42
	v_cvt_f32_i32_e32 v43, v43
	v_cvt_f32_i32_e32 v36, v36
	v_cvt_f32_i32_e32 v37, v37
	v_cvt_f32_i32_e32 v38, v38
	v_cvt_f32_i32_e32 v39, v39
	v_cvt_f32_i32_e32 v28, v28
	v_cvt_f32_i32_e32 v29, v29
	v_cvt_f32_i32_e32 v30, v30
	v_cvt_f32_i32_e32 v31, v31
	v_cvt_f32_i32_e32 v32, v32
	v_cvt_f32_i32_e32 v33, v33
	v_cvt_f32_i32_e32 v34, v34
	v_cvt_f32_i32_e32 v35, v35
	v_cvt_f32_i32_e32 v24, v24
	v_cvt_f32_i32_e32 v25, v25
	v_cvt_f32_i32_e32 v26, v26
	v_cvt_f32_i32_e32 v27, v27
	v_cvt_f32_i32_e32 v20, v20
	v_cvt_f32_i32_e32 v21, v21
	v_cvt_f32_i32_e32 v22, v22
	v_cvt_f32_i32_e32 v23, v23
	v_cvt_f32_i32_e32 v16, v16
	v_cvt_f32_i32_e32 v17, v17
	v_cvt_f32_i32_e32 v18, v18
	v_cvt_f32_i32_e32 v19, v19
	v_cvt_f32_i32_e32 v12, v12
	v_cvt_f32_i32_e32 v13, v13
	v_cvt_f32_i32_e32 v14, v14
	v_cvt_f32_i32_e32 v15, v15
	v_cvt_f32_i32_e32 v8, v8
	v_cvt_f32_i32_e32 v9, v9
	v_cvt_f32_i32_e32 v10, v10
	v_cvt_f32_i32_e32 v11, v11
	v_cvt_f32_i32_e32 v4, v4
	v_cvt_f32_i32_e32 v5, v5
	v_cvt_f32_i32_e32 v6, v6
	v_cvt_f32_i32_e32 v7, v7
	v_cvt_f32_i32_e32 v0, v0
	v_cvt_f32_i32_e32 v1, v1
	v_cvt_f32_i32_e32 v2, v2
	v_cvt_f32_i32_e32 v3, v3
	s_waitcnt vmcnt(0)
	v_add_u32_e32 v96, s12, v117
	v_or_b32_e32 v146, s13, v118
	v_lshl_add_u64 v[144:145], v[96:97], 2, s[68:69]
	v_lshlrev_b32_e32 v148, 2, v146
	global_load_dword v136, v[144:145], off
	global_load_dword v138, v[144:145], off offset:64
	global_load_dword v140, v[144:145], off offset:128
	global_load_dword v142, v[144:145], off offset:192
	global_load_dwordx4 v[120:123], v148, s[0:1]
	global_load_dwordx4 v[124:127], v148, s[0:1] offset:64
	global_load_dwordx4 v[128:131], v148, s[0:1] offset:128
	global_load_dwordx4 v[132:135], v148, s[0:1] offset:192
	v_lshlrev_b32_e32 v146, 1, v146
	v_mov_b32_e32 v147, v97
	v_lshlrev_b64 v[44:45], 12, v[96:97]
	v_lshl_add_u64 v[44:45], s[64:65], 0, v[44:45]
	v_lshl_add_u64 v[44:45], v[44:45], 0, v[146:147]
	v_or_b32_e32 v52, 16, v96
	v_mov_b32_e32 v53, v97
	v_lshlrev_b64 v[46:47], 12, v[52:53]
	v_lshl_add_u64 v[46:47], s[64:65], 0, v[46:47]
	v_lshl_add_u64 v[46:47], v[46:47], 0, v[146:147]
	v_or_b32_e32 v52, 32, v96
	v_mov_b32_e32 v53, v97
	v_lshlrev_b64 v[48:49], 12, v[52:53]
	v_lshl_add_u64 v[48:49], s[64:65], 0, v[48:49]
	v_lshl_add_u64 v[48:49], v[48:49], 0, v[146:147]
	v_or_b32_e32 v52, 48, v96
	v_mov_b32_e32 v53, v97
	v_lshlrev_b64 v[50:51], 12, v[52:53]
	v_lshl_add_u64 v[50:51], s[64:65], 0, v[50:51]
	v_lshl_add_u64 v[50:51], v[50:51], 0, v[146:147]
	s_waitcnt vmcnt(0)
	v_pk_mul_f32 v[92:93], v[136:137], v[92:93] op_sel_hi:[0,1]
	v_pk_mul_f32 v[94:95], v[136:137], v[94:95] op_sel_hi:[0,1]
	v_pk_mul_f32 v[92:93], v[120:121], v[92:93]
	v_pk_mul_f32 v[94:95], v[94:95], v[122:123]
	v_cvt_pk_bf16_f32 v92, v92, v93
	v_cvt_pk_bf16_f32 v93, v94, v95
	global_store_dwordx2 v[44:45], v[92:93], off
	v_pk_mul_f32 v[88:89], v[136:137], v[88:89] op_sel_hi:[0,1]
	v_pk_mul_f32 v[90:91], v[136:137], v[90:91] op_sel_hi:[0,1]
	v_pk_mul_f32 v[88:89], v[124:125], v[88:89]
	v_pk_mul_f32 v[90:91], v[90:91], v[126:127]
	v_cvt_pk_bf16_f32 v88, v88, v89
	v_cvt_pk_bf16_f32 v89, v90, v91
	global_store_dwordx2 v[44:45], v[88:89], off offset:32
	v_pk_mul_f32 v[84:85], v[136:137], v[84:85] op_sel_hi:[0,1]
	v_pk_mul_f32 v[86:87], v[136:137], v[86:87] op_sel_hi:[0,1]
	v_pk_mul_f32 v[84:85], v[128:129], v[84:85]
	v_pk_mul_f32 v[86:87], v[86:87], v[130:131]
	v_cvt_pk_bf16_f32 v84, v84, v85
	v_cvt_pk_bf16_f32 v85, v86, v87
	global_store_dwordx2 v[44:45], v[84:85], off offset:64
	v_pk_mul_f32 v[80:81], v[136:137], v[80:81] op_sel_hi:[0,1]
	v_pk_mul_f32 v[82:83], v[136:137], v[82:83] op_sel_hi:[0,1]
	v_pk_mul_f32 v[80:81], v[132:133], v[80:81]
	v_pk_mul_f32 v[82:83], v[82:83], v[134:135]
	v_cvt_pk_bf16_f32 v80, v80, v81
	v_cvt_pk_bf16_f32 v81, v82, v83
	global_store_dwordx2 v[44:45], v[80:81], off offset:96
	v_pk_mul_f32 v[60:61], v[138:139], v[60:61] op_sel_hi:[0,1]
	v_pk_mul_f32 v[62:63], v[138:139], v[62:63] op_sel_hi:[0,1]
	v_pk_mul_f32 v[60:61], v[120:121], v[60:61]
	v_pk_mul_f32 v[62:63], v[62:63], v[122:123]
	v_cvt_pk_bf16_f32 v60, v60, v61
	v_cvt_pk_bf16_f32 v61, v62, v63
	global_store_dwordx2 v[46:47], v[60:61], off
	v_pk_mul_f32 v[40:41], v[138:139], v[40:41] op_sel_hi:[0,1]
	v_pk_mul_f32 v[42:43], v[138:139], v[42:43] op_sel_hi:[0,1]
	v_pk_mul_f32 v[40:41], v[124:125], v[40:41]
	v_pk_mul_f32 v[42:43], v[42:43], v[126:127]
	v_cvt_pk_bf16_f32 v40, v40, v41
	v_cvt_pk_bf16_f32 v41, v42, v43
	global_store_dwordx2 v[46:47], v[40:41], off offset:32
	v_pk_mul_f32 v[36:37], v[138:139], v[36:37] op_sel_hi:[0,1]
	v_pk_mul_f32 v[38:39], v[138:139], v[38:39] op_sel_hi:[0,1]
	v_pk_mul_f32 v[36:37], v[128:129], v[36:37]
	v_pk_mul_f32 v[38:39], v[38:39], v[130:131]
	v_cvt_pk_bf16_f32 v36, v36, v37
	v_cvt_pk_bf16_f32 v37, v38, v39
	global_store_dwordx2 v[46:47], v[36:37], off offset:64
	v_pk_mul_f32 v[28:29], v[138:139], v[28:29] op_sel_hi:[0,1]
	v_pk_mul_f32 v[30:31], v[138:139], v[30:31] op_sel_hi:[0,1]
	v_pk_mul_f32 v[28:29], v[132:133], v[28:29]
	v_pk_mul_f32 v[30:31], v[30:31], v[134:135]
	v_cvt_pk_bf16_f32 v28, v28, v29
	v_cvt_pk_bf16_f32 v29, v30, v31
	global_store_dwordx2 v[46:47], v[28:29], off offset:96
	v_pk_mul_f32 v[32:33], v[140:141], v[32:33] op_sel_hi:[0,1]
	v_pk_mul_f32 v[34:35], v[140:141], v[34:35] op_sel_hi:[0,1]
	v_pk_mul_f32 v[32:33], v[120:121], v[32:33]
	v_pk_mul_f32 v[34:35], v[34:35], v[122:123]
	v_cvt_pk_bf16_f32 v32, v32, v33
	v_cvt_pk_bf16_f32 v33, v34, v35
	global_store_dwordx2 v[48:49], v[32:33], off
	v_pk_mul_f32 v[24:25], v[140:141], v[24:25] op_sel_hi:[0,1]
	v_pk_mul_f32 v[26:27], v[140:141], v[26:27] op_sel_hi:[0,1]
	v_pk_mul_f32 v[24:25], v[124:125], v[24:25]
	v_pk_mul_f32 v[26:27], v[26:27], v[126:127]
	v_cvt_pk_bf16_f32 v24, v24, v25
	v_cvt_pk_bf16_f32 v25, v26, v27
	global_store_dwordx2 v[48:49], v[24:25], off offset:32
	v_pk_mul_f32 v[20:21], v[140:141], v[20:21] op_sel_hi:[0,1]
	v_pk_mul_f32 v[22:23], v[140:141], v[22:23] op_sel_hi:[0,1]
	v_pk_mul_f32 v[20:21], v[128:129], v[20:21]
	v_pk_mul_f32 v[22:23], v[22:23], v[130:131]
	v_cvt_pk_bf16_f32 v20, v20, v21
	v_cvt_pk_bf16_f32 v21, v22, v23
	global_store_dwordx2 v[48:49], v[20:21], off offset:64
	v_pk_mul_f32 v[16:17], v[140:141], v[16:17] op_sel_hi:[0,1]
	v_pk_mul_f32 v[18:19], v[140:141], v[18:19] op_sel_hi:[0,1]
	v_pk_mul_f32 v[16:17], v[132:133], v[16:17]
	v_pk_mul_f32 v[18:19], v[18:19], v[134:135]
	v_cvt_pk_bf16_f32 v16, v16, v17
	v_cvt_pk_bf16_f32 v17, v18, v19
	global_store_dwordx2 v[48:49], v[16:17], off offset:96
	v_pk_mul_f32 v[12:13], v[142:143], v[12:13] op_sel_hi:[0,1]
	v_pk_mul_f32 v[14:15], v[142:143], v[14:15] op_sel_hi:[0,1]
	v_pk_mul_f32 v[12:13], v[120:121], v[12:13]
	v_pk_mul_f32 v[14:15], v[14:15], v[122:123]
	v_cvt_pk_bf16_f32 v12, v12, v13
	v_cvt_pk_bf16_f32 v13, v14, v15
	global_store_dwordx2 v[50:51], v[12:13], off
	v_pk_mul_f32 v[8:9], v[142:143], v[8:9] op_sel_hi:[0,1]
	v_pk_mul_f32 v[10:11], v[142:143], v[10:11] op_sel_hi:[0,1]
	v_pk_mul_f32 v[8:9], v[124:125], v[8:9]
	v_pk_mul_f32 v[10:11], v[10:11], v[126:127]
	v_cvt_pk_bf16_f32 v8, v8, v9
	v_cvt_pk_bf16_f32 v9, v10, v11
	global_store_dwordx2 v[50:51], v[8:9], off offset:32
	v_pk_mul_f32 v[4:5], v[142:143], v[4:5] op_sel_hi:[0,1]
	v_pk_mul_f32 v[6:7], v[142:143], v[6:7] op_sel_hi:[0,1]
	v_pk_mul_f32 v[4:5], v[128:129], v[4:5]
	v_pk_mul_f32 v[6:7], v[6:7], v[130:131]
	v_cvt_pk_bf16_f32 v4, v4, v5
	v_cvt_pk_bf16_f32 v5, v6, v7
	global_store_dwordx2 v[50:51], v[4:5], off offset:64
	v_pk_mul_f32 v[0:1], v[142:143], v[0:1] op_sel_hi:[0,1]
	v_pk_mul_f32 v[2:3], v[142:143], v[2:3] op_sel_hi:[0,1]
	v_pk_mul_f32 v[0:1], v[132:133], v[0:1]
	v_pk_mul_f32 v[2:3], v[2:3], v[134:135]
	v_cvt_pk_bf16_f32 v0, v0, v1
	v_cvt_pk_bf16_f32 v1, v2, v3
	global_store_dwordx2 v[50:51], v[0:1], off offset:96
	s_add_i32 s8, s8, s3
	s_cmpk_lt_u32 s8, 0x200
	s_cbranch_scc1 .LBB0_889
